# S5 pass2 recurrence: counted lgkmcnt(15) wait before each step instead of draining all sixteen reads first
# speedup vs baseline: 1.0012x; 1.0012x over previous
.LBB0_1787:
	s_or_b64 exec, exec, s[0:1]
	s_movk_i32 s1, 0x3200
	v_mul_lo_u32 v72, v82, s1
	v_add_u32_e32 v81, 0, v72
	s_waitcnt vmcnt(0) lgkmcnt(0)
	v_mov_b32_e32 v158, 0x5040100
	v_mov_b32_e32 v159, 0x7060302
	v_perm_b32 v24, v142, v140, v158
	v_perm_b32 v25, v142, v140, v159
	v_perm_b32 v26, v143, v141, v158
	v_perm_b32 v27, v143, v141, v159
	v_perm_b32 v20, v146, v144, v158
	v_perm_b32 v21, v146, v144, v159
	v_perm_b32 v22, v147, v145, v158
	v_perm_b32 v23, v147, v145, v159
	v_perm_b32 v16, v150, v148, v158
	v_perm_b32 v17, v150, v148, v159
	v_perm_b32 v18, v151, v149, v158
	v_perm_b32 v19, v151, v149, v159
	v_perm_b32 v12, v154, v152, v158
	v_perm_b32 v13, v154, v152, v159
	v_perm_b32 v14, v155, v153, v158
	v_perm_b32 v15, v155, v153, v159
	v_mfma_f32_16x16x32_bf16 v[84:87], v[0:3], v[32:35], 0
	v_mul_u32_u24_e32 v72, 0x210, v83
	v_lshlrev_b32_e32 v73, 2, v79
	v_lshlrev_b32_e32 v72, 2, v72
	v_mfma_f32_16x16x32_bf16 v[96:99], v[0:3], v[28:31], 0
	v_add3_u32 v73, v81, v73, v72
	v_add_u32_e32 v74, 0x400, v73
	s_nop 5
	ds_write2_b32 v73, v84, v96 offset1:16
	ds_write2_b32 v73, v85, v97 offset0:132 offset1:148
	ds_write2_b32 v74, v86, v98 offset0:8 offset1:24
	ds_write2_b32 v74, v87, v99 offset0:140 offset1:156
	v_mfma_f32_16x16x32_bf16 v[82:85], v[0:3], v[40:43], 0
	v_lshl_add_u32 v75, v78, 2, v81
	s_cmp_gt_i32 s9, 3
	s_cselect_b32 s0, 0x87, 3
	v_mfma_f32_16x16x32_bf16 v[86:89], v[0:3], v[36:39], 0
	s_nop 7
	ds_write2_b32 v73, v82, v86 offset0:32 offset1:48
	ds_write2_b32 v73, v83, v87 offset0:164 offset1:180
	ds_write2_b32 v74, v84, v88 offset0:40 offset1:56
	ds_write2_b32 v74, v85, v89 offset0:172 offset1:188
	v_mfma_f32_16x16x32_bf16 v[82:85], v[0:3], v[48:51], 0
	s_sub_i32 s0, s0, s9
	v_mul_u32_u24_e32 v94, 0x110, v79
	v_add_u32_e32 v79, 64, v75
	v_mfma_f32_16x16x32_bf16 v[86:89], v[0:3], v[44:47], 0
	s_nop 7
	ds_write2_b32 v73, v82, v86 offset0:64 offset1:80
	ds_write2_b32 v73, v83, v87 offset0:196 offset1:212
	ds_write2_b32 v74, v84, v88 offset0:72 offset1:88
	ds_write2_b32 v74, v85, v89 offset0:204 offset1:220
	v_mfma_f32_16x16x32_bf16 v[82:85], v[0:3], v[56:59], 0
	v_add_u32_e32 v86, 0x90, v75
	v_add_u32_e32 v87, 0xa0, v75
	v_add_u32_e32 v88, 0xb0, v75
	v_mfma_f32_16x16x32_bf16 v[0:3], v[0:3], v[52:55], 0
	s_nop 7
	ds_write2_b32 v73, v82, v0 offset0:96 offset1:112
	ds_write2_b32 v73, v83, v1 offset0:228 offset1:244
	ds_write2_b32 v74, v84, v2 offset0:104 offset1:120
	ds_write2_b32 v74, v85, v3 offset0:236 offset1:252
	v_lshlrev_b32_e32 v0, 1, v78
	s_waitcnt vmcnt(0) lgkmcnt(0)
	v_sub_u32_e32 v72, v75, v0
	ds_read2st64_b32 v[0:1], v75 offset1:1
	ds_read2_b32 v[140:141], v75 offset0:132 offset1:196
	v_add_u32_e32 v142, 32, v75
	ds_read2st64_b32 v[144:145], v142 offset0:4 offset1:5
	v_add_u32_e32 v143, 48, v75
	ds_read2st64_b32 v[146:147], v143 offset0:6 offset1:7
	ds_read2st64_b32 v[148:149], v79 offset0:8 offset1:9
	v_add_u32_e32 v150, 0x50, v75
	ds_read2st64_b32 v[152:153], v150 offset0:10 offset1:11
	v_add_u32_e32 v151, 0x60, v75
	ds_read2st64_b32 v[154:155], v151 offset0:12 offset1:13
	v_add_u32_e32 v156, 0x70, v75
	ds_read2st64_b32 v[158:159], v156 offset0:14 offset1:15
	v_add_u32_e32 v157, 0x80, v75
	ds_read2st64_b32 v[160:161], v157 offset0:16 offset1:17
	ds_read2st64_b32 v[162:163], v86 offset0:18 offset1:19
	ds_read2st64_b32 v[164:165], v87 offset0:20 offset1:21
	ds_read2st64_b32 v[166:167], v88 offset0:22 offset1:23
	v_add_u32_e32 v168, 0xc0, v75
	ds_read2st64_b32 v[170:171], v168 offset0:24 offset1:25
	v_add_u32_e32 v169, 0xd0, v75
	ds_read2st64_b32 v[172:173], v169 offset0:26 offset1:27
	v_add_u32_e32 v174, 0xe0, v75
	ds_read2st64_b32 v[176:177], v174 offset0:28 offset1:29
	v_add_u32_e32 v175, 0xf0, v75
	ds_read2st64_b32 v[178:179], v175 offset0:30 offset1:31
	v_mov_b32_e32 v186, v70
	v_mov_b32_e32 v187, v71
	v_add_u32_e32 v78, 48, v75
	v_add_u32_e32 v82, 0x50, v75
	s_waitcnt lgkmcnt(15)
	v_pk_fma_f32 v[184:185], v[66:67], v[186:187], v[0:1] op_sel:[1,1,0] op_sel_hi:[1,0,1] neg_lo:[1,0,0]
	v_pk_fma_f32 v[188:189], v[66:67], v[186:187], v[184:185] op_sel_hi:[0,1,1]
	v_cvt_pk_bf16_f32 v190, v188, v189
	v_and_b32_e32 v191, 63, v207
	v_lshl_add_u32 v191, v191, 1, v72
	ds_write_b32 v191, v190 offset:8448
	v_add_u32_e32 v71, 32, v75
	v_add_u32_e32 v83, 0x60, v75
	s_waitcnt lgkmcnt(15)
	v_pk_fma_f32 v[184:185], v[66:67], v[188:189], v[140:141] op_sel:[1,1,0] op_sel_hi:[1,0,1] neg_lo:[1,0,0]
	v_pk_fma_f32 v[186:187], v[66:67], v[188:189], v[184:185] op_sel_hi:[0,1,1]
	v_cvt_pk_bf16_f32 v190, v186, v187
	ds_write_b32 v191, v190 offset:8720
	v_add_u32_e32 v84, 0x70, v75
	v_add_u32_e32 v85, 0x80, v75
	s_waitcnt lgkmcnt(15)
	v_pk_fma_f32 v[184:185], v[66:67], v[186:187], v[144:145] op_sel:[1,1,0] op_sel_hi:[1,0,1] neg_lo:[1,0,0]
	v_pk_fma_f32 v[188:189], v[66:67], v[186:187], v[184:185] op_sel_hi:[0,1,1]
	v_cvt_pk_bf16_f32 v190, v188, v189
	ds_write_b32 v191, v190 offset:8992
	v_add_u32_e32 v89, 0xc0, v75
	v_add_u32_e32 v91, 0xd0, v75
	s_waitcnt lgkmcnt(15)
	v_pk_fma_f32 v[184:185], v[66:67], v[188:189], v[146:147] op_sel:[1,1,0] op_sel_hi:[1,0,1] neg_lo:[1,0,0]
	v_pk_fma_f32 v[186:187], v[66:67], v[188:189], v[184:185] op_sel_hi:[0,1,1]
	v_cvt_pk_bf16_f32 v190, v186, v187
	ds_write_b32 v191, v190 offset:9264
	v_add_u32_e32 v92, 0xe0, v75
	v_add_u32_e32 v93, 0xf0, v75
	s_waitcnt lgkmcnt(15)
	v_pk_fma_f32 v[184:185], v[66:67], v[186:187], v[148:149] op_sel:[1,1,0] op_sel_hi:[1,0,1] neg_lo:[1,0,0]
	v_pk_fma_f32 v[188:189], v[66:67], v[186:187], v[184:185] op_sel_hi:[0,1,1]
	v_cvt_pk_bf16_f32 v190, v188, v189
	ds_write_b32 v191, v190 offset:9536
	v_mfma_f32_16x16x32_bf16 v[98:101], v[4:7], v[28:31], 0
	s_or_b32 s1, s2, 0x84
	s_waitcnt lgkmcnt(15)
	v_pk_fma_f32 v[184:185], v[66:67], v[188:189], v[152:153] op_sel:[1,1,0] op_sel_hi:[1,0,1] neg_lo:[1,0,0]
	v_pk_fma_f32 v[186:187], v[66:67], v[188:189], v[184:185] op_sel_hi:[0,1,1]
	v_cvt_pk_bf16_f32 v190, v186, v187
	ds_write_b32 v191, v190 offset:9808
	s_ashr_i32 s2, s0, 31
	s_waitcnt lgkmcnt(15)
	v_pk_fma_f32 v[184:185], v[66:67], v[186:187], v[154:155] op_sel:[1,1,0] op_sel_hi:[1,0,1] neg_lo:[1,0,0]
	v_pk_fma_f32 v[188:189], v[66:67], v[186:187], v[184:185] op_sel_hi:[0,1,1]
	v_cvt_pk_bf16_f32 v190, v188, v189
	ds_write_b32 v191, v190 offset:10080
	s_waitcnt lgkmcnt(15)
	v_pk_fma_f32 v[184:185], v[66:67], v[188:189], v[158:159] op_sel:[1,1,0] op_sel_hi:[1,0,1] neg_lo:[1,0,0]
	v_pk_fma_f32 v[186:187], v[66:67], v[188:189], v[184:185] op_sel_hi:[0,1,1]
	v_cvt_pk_bf16_f32 v190, v186, v187
	ds_write_b32 v191, v190 offset:10352
	s_waitcnt lgkmcnt(15)
	v_pk_fma_f32 v[184:185], v[66:67], v[186:187], v[160:161] op_sel:[1,1,0] op_sel_hi:[1,0,1] neg_lo:[1,0,0]
	v_pk_fma_f32 v[188:189], v[66:67], v[186:187], v[184:185] op_sel_hi:[0,1,1]
	v_cvt_pk_bf16_f32 v190, v188, v189
	ds_write_b32 v191, v190 offset:10624
	s_waitcnt lgkmcnt(15)
	v_pk_fma_f32 v[184:185], v[66:67], v[188:189], v[162:163] op_sel:[1,1,0] op_sel_hi:[1,0,1] neg_lo:[1,0,0]
	v_pk_fma_f32 v[186:187], v[66:67], v[188:189], v[184:185] op_sel_hi:[0,1,1]
	v_cvt_pk_bf16_f32 v190, v186, v187
	ds_write_b32 v191, v190 offset:10896
	s_waitcnt lgkmcnt(15)
	v_pk_fma_f32 v[184:185], v[66:67], v[186:187], v[164:165] op_sel:[1,1,0] op_sel_hi:[1,0,1] neg_lo:[1,0,0]
	v_pk_fma_f32 v[188:189], v[66:67], v[186:187], v[184:185] op_sel_hi:[0,1,1]
	v_cvt_pk_bf16_f32 v190, v188, v189
	ds_write_b32 v191, v190 offset:11168
	s_waitcnt lgkmcnt(15)
	v_pk_fma_f32 v[184:185], v[66:67], v[188:189], v[166:167] op_sel:[1,1,0] op_sel_hi:[1,0,1] neg_lo:[1,0,0]
	v_pk_fma_f32 v[186:187], v[66:67], v[188:189], v[184:185] op_sel_hi:[0,1,1]
	v_cvt_pk_bf16_f32 v190, v186, v187
	ds_write_b32 v191, v190 offset:11440
	s_waitcnt lgkmcnt(15)
	v_pk_fma_f32 v[184:185], v[66:67], v[186:187], v[170:171] op_sel:[1,1,0] op_sel_hi:[1,0,1] neg_lo:[1,0,0]
	v_pk_fma_f32 v[188:189], v[66:67], v[186:187], v[184:185] op_sel_hi:[0,1,1]
	v_cvt_pk_bf16_f32 v190, v188, v189
	ds_write_b32 v191, v190 offset:11712
	s_waitcnt lgkmcnt(15)
	v_pk_fma_f32 v[184:185], v[66:67], v[188:189], v[172:173] op_sel:[1,1,0] op_sel_hi:[1,0,1] neg_lo:[1,0,0]
	v_pk_fma_f32 v[186:187], v[66:67], v[188:189], v[184:185] op_sel_hi:[0,1,1]
	v_cvt_pk_bf16_f32 v190, v186, v187
	ds_write_b32 v191, v190 offset:11984
	s_waitcnt lgkmcnt(15)
	v_pk_fma_f32 v[184:185], v[66:67], v[186:187], v[176:177] op_sel:[1,1,0] op_sel_hi:[1,0,1] neg_lo:[1,0,0]
	v_pk_fma_f32 v[188:189], v[66:67], v[186:187], v[184:185] op_sel_hi:[0,1,1]
	v_cvt_pk_bf16_f32 v190, v188, v189
	ds_write_b32 v191, v190 offset:12256
	s_waitcnt lgkmcnt(15)
	v_pk_fma_f32 v[184:185], v[66:67], v[188:189], v[178:179] op_sel:[1,1,0] op_sel_hi:[1,0,1] neg_lo:[1,0,0]
	v_pk_fma_f32 v[186:187], v[66:67], v[188:189], v[184:185] op_sel_hi:[0,1,1]
	v_mov_b32_e32 v102, v186
	v_mov_b32_e32 v103, v187
	v_cvt_pk_bf16_f32 v190, v186, v187
	ds_write_b32 v191, v190 offset:12528
	v_add3_u32 v70, v81, v128, v94
	s_waitcnt vmcnt(0) lgkmcnt(0)
	ds_read_b128 v[0:3], v70 offset:8448
	ds_read_b128 v[94:97], v70 offset:8512
	s_waitcnt lgkmcnt(1)
	v_mfma_f32_16x16x32_bf16 v[0:3], v[0:3], v[24:27], 0
	s_waitcnt lgkmcnt(0)
	v_mfma_f32_16x16x32_bf16 v[0:3], v[94:97], v[20:23], v[0:3]
	ds_read_b128 v[94:97], v70 offset:8576
	s_waitcnt lgkmcnt(0)
	v_mfma_f32_16x16x32_bf16 v[0:3], v[94:97], v[16:19], v[0:3]
	ds_read_b128 v[94:97], v70 offset:8640
	s_waitcnt lgkmcnt(0)
	v_mfma_f32_16x16x32_bf16 v[0:3], v[94:97], v[12:15], v[0:3]
	v_mfma_f32_16x16x32_bf16 v[94:97], v[4:7], v[32:35], 0
	s_nop 7
	ds_write2_b32 v73, v94, v98 offset1:16
	ds_write2_b32 v73, v95, v99 offset0:132 offset1:148
	ds_write2_b32 v74, v96, v100 offset0:8 offset1:24
	ds_write2_b32 v74, v97, v101 offset0:140 offset1:156
	v_mfma_f32_16x16x32_bf16 v[94:97], v[4:7], v[40:43], 0
	v_mfma_f32_16x16x32_bf16 v[98:101], v[4:7], v[36:39], 0
	s_nop 7
	ds_write2_b32 v73, v94, v98 offset0:32 offset1:48
	ds_write2_b32 v73, v95, v99 offset0:164 offset1:180
	ds_write2_b32 v74, v96, v100 offset0:40 offset1:56
	ds_write2_b32 v74, v97, v101 offset0:172 offset1:188
	v_mfma_f32_16x16x32_bf16 v[94:97], v[4:7], v[48:51], 0
	v_mfma_f32_16x16x32_bf16 v[98:101], v[4:7], v[44:47], 0
	s_nop 7
	ds_write2_b32 v73, v94, v98 offset0:64 offset1:80
	ds_write2_b32 v73, v95, v99 offset0:196 offset1:212
	ds_write2_b32 v74, v96, v100 offset0:72 offset1:88
	ds_write2_b32 v74, v97, v101 offset0:204 offset1:220
	v_mfma_f32_16x16x32_bf16 v[94:97], v[4:7], v[56:59], 0
	v_mfma_f32_16x16x32_bf16 v[4:7], v[4:7], v[52:55], 0
	s_nop 7
	ds_write2_b32 v73, v94, v4 offset0:96 offset1:112
	ds_write2_b32 v73, v95, v5 offset0:228 offset1:244
	ds_write2_b32 v74, v96, v6 offset0:104 offset1:120
	ds_write2_b32 v74, v97, v7 offset0:236 offset1:252
	s_waitcnt vmcnt(0) lgkmcnt(0)
	ds_read2st64_b32 v[4:5], v75 offset1:1
	ds_read2_b32 v[140:141], v75 offset0:132 offset1:196
	ds_read2st64_b32 v[142:143], v71 offset0:4 offset1:5
	ds_read2st64_b32 v[144:145], v78 offset0:6 offset1:7
	ds_read2st64_b32 v[146:147], v79 offset0:8 offset1:9
	ds_read2st64_b32 v[148:149], v82 offset0:10 offset1:11
	ds_read2st64_b32 v[150:151], v83 offset0:12 offset1:13
	ds_read2st64_b32 v[152:153], v84 offset0:14 offset1:15
	ds_read2st64_b32 v[154:155], v85 offset0:16 offset1:17
	ds_read2st64_b32 v[156:157], v86 offset0:18 offset1:19
	ds_read2st64_b32 v[158:159], v87 offset0:20 offset1:21
	ds_read2st64_b32 v[160:161], v88 offset0:22 offset1:23
	ds_read2st64_b32 v[162:163], v89 offset0:24 offset1:25
	ds_read2st64_b32 v[164:165], v91 offset0:26 offset1:27
	ds_read2st64_b32 v[166:167], v92 offset0:28 offset1:29
	ds_read2st64_b32 v[168:169], v93 offset0:30 offset1:31
	v_mov_b32_e32 v186, v102
	v_mov_b32_e32 v187, v103
	v_mfma_f32_16x16x32_bf16 v[98:101], v[8:11], v[28:31], 0
	s_waitcnt lgkmcnt(15)
	v_pk_fma_f32 v[184:185], v[66:67], v[186:187], v[4:5] op_sel:[1,1,0] op_sel_hi:[1,0,1] neg_lo:[1,0,0]
	v_pk_fma_f32 v[188:189], v[66:67], v[186:187], v[184:185] op_sel_hi:[0,1,1]
	v_cvt_pk_bf16_f32 v190, v188, v189
	v_and_b32_e32 v191, 63, v207
	v_lshl_add_u32 v191, v191, 1, v72
	ds_write_b32 v191, v190 offset:8448
	v_mfma_f32_16x16x32_bf16 v[28:31], v[60:63], v[28:31], 0
	s_waitcnt lgkmcnt(15)
	v_pk_fma_f32 v[184:185], v[66:67], v[188:189], v[140:141] op_sel:[1,1,0] op_sel_hi:[1,0,1] neg_lo:[1,0,0]
	v_pk_fma_f32 v[186:187], v[66:67], v[188:189], v[184:185] op_sel_hi:[0,1,1]
	v_cvt_pk_bf16_f32 v190, v186, v187
	ds_write_b32 v191, v190 offset:8720
	s_waitcnt lgkmcnt(15)
	v_pk_fma_f32 v[184:185], v[66:67], v[186:187], v[142:143] op_sel:[1,1,0] op_sel_hi:[1,0,1] neg_lo:[1,0,0]
	v_pk_fma_f32 v[188:189], v[66:67], v[186:187], v[184:185] op_sel_hi:[0,1,1]
	v_cvt_pk_bf16_f32 v190, v188, v189
	ds_write_b32 v191, v190 offset:8992
	s_waitcnt lgkmcnt(15)
	v_pk_fma_f32 v[184:185], v[66:67], v[188:189], v[144:145] op_sel:[1,1,0] op_sel_hi:[1,0,1] neg_lo:[1,0,0]
	v_pk_fma_f32 v[186:187], v[66:67], v[188:189], v[184:185] op_sel_hi:[0,1,1]
	v_cvt_pk_bf16_f32 v190, v186, v187
	ds_write_b32 v191, v190 offset:9264
	s_waitcnt lgkmcnt(15)
	v_pk_fma_f32 v[184:185], v[66:67], v[186:187], v[146:147] op_sel:[1,1,0] op_sel_hi:[1,0,1] neg_lo:[1,0,0]
	v_pk_fma_f32 v[188:189], v[66:67], v[186:187], v[184:185] op_sel_hi:[0,1,1]
	v_cvt_pk_bf16_f32 v190, v188, v189
	ds_write_b32 v191, v190 offset:9536
	s_waitcnt lgkmcnt(15)
	v_pk_fma_f32 v[184:185], v[66:67], v[188:189], v[148:149] op_sel:[1,1,0] op_sel_hi:[1,0,1] neg_lo:[1,0,0]
	v_pk_fma_f32 v[186:187], v[66:67], v[188:189], v[184:185] op_sel_hi:[0,1,1]
	v_cvt_pk_bf16_f32 v190, v186, v187
	ds_write_b32 v191, v190 offset:9808
	s_waitcnt lgkmcnt(15)
	v_pk_fma_f32 v[184:185], v[66:67], v[186:187], v[150:151] op_sel:[1,1,0] op_sel_hi:[1,0,1] neg_lo:[1,0,0]
	v_pk_fma_f32 v[188:189], v[66:67], v[186:187], v[184:185] op_sel_hi:[0,1,1]
	v_cvt_pk_bf16_f32 v190, v188, v189
	ds_write_b32 v191, v190 offset:10080
	s_waitcnt lgkmcnt(15)
	v_pk_fma_f32 v[184:185], v[66:67], v[188:189], v[152:153] op_sel:[1,1,0] op_sel_hi:[1,0,1] neg_lo:[1,0,0]
	v_pk_fma_f32 v[186:187], v[66:67], v[188:189], v[184:185] op_sel_hi:[0,1,1]
	v_cvt_pk_bf16_f32 v190, v186, v187
	ds_write_b32 v191, v190 offset:10352
	s_waitcnt lgkmcnt(15)
	v_pk_fma_f32 v[184:185], v[66:67], v[186:187], v[154:155] op_sel:[1,1,0] op_sel_hi:[1,0,1] neg_lo:[1,0,0]
	v_pk_fma_f32 v[188:189], v[66:67], v[186:187], v[184:185] op_sel_hi:[0,1,1]
	v_cvt_pk_bf16_f32 v190, v188, v189
	ds_write_b32 v191, v190 offset:10624
	s_waitcnt lgkmcnt(15)
	v_pk_fma_f32 v[184:185], v[66:67], v[188:189], v[156:157] op_sel:[1,1,0] op_sel_hi:[1,0,1] neg_lo:[1,0,0]
	v_pk_fma_f32 v[186:187], v[66:67], v[188:189], v[184:185] op_sel_hi:[0,1,1]
	v_cvt_pk_bf16_f32 v190, v186, v187
	ds_write_b32 v191, v190 offset:10896
	s_waitcnt lgkmcnt(15)
	v_pk_fma_f32 v[184:185], v[66:67], v[186:187], v[158:159] op_sel:[1,1,0] op_sel_hi:[1,0,1] neg_lo:[1,0,0]
	v_pk_fma_f32 v[188:189], v[66:67], v[186:187], v[184:185] op_sel_hi:[0,1,1]
	v_cvt_pk_bf16_f32 v190, v188, v189
	ds_write_b32 v191, v190 offset:11168
	s_waitcnt lgkmcnt(15)
	v_pk_fma_f32 v[184:185], v[66:67], v[188:189], v[160:161] op_sel:[1,1,0] op_sel_hi:[1,0,1] neg_lo:[1,0,0]
	v_pk_fma_f32 v[186:187], v[66:67], v[188:189], v[184:185] op_sel_hi:[0,1,1]
	v_cvt_pk_bf16_f32 v190, v186, v187
	ds_write_b32 v191, v190 offset:11440
	s_waitcnt lgkmcnt(15)
	v_pk_fma_f32 v[184:185], v[66:67], v[186:187], v[162:163] op_sel:[1,1,0] op_sel_hi:[1,0,1] neg_lo:[1,0,0]
	v_pk_fma_f32 v[188:189], v[66:67], v[186:187], v[184:185] op_sel_hi:[0,1,1]
	v_cvt_pk_bf16_f32 v190, v188, v189
	ds_write_b32 v191, v190 offset:11712
	s_waitcnt lgkmcnt(15)
	v_pk_fma_f32 v[184:185], v[66:67], v[188:189], v[164:165] op_sel:[1,1,0] op_sel_hi:[1,0,1] neg_lo:[1,0,0]
	v_pk_fma_f32 v[186:187], v[66:67], v[188:189], v[184:185] op_sel_hi:[0,1,1]
	v_cvt_pk_bf16_f32 v190, v186, v187
	ds_write_b32 v191, v190 offset:11984
	s_waitcnt lgkmcnt(15)
	v_pk_fma_f32 v[184:185], v[66:67], v[186:187], v[166:167] op_sel:[1,1,0] op_sel_hi:[1,0,1] neg_lo:[1,0,0]
	v_pk_fma_f32 v[188:189], v[66:67], v[186:187], v[184:185] op_sel_hi:[0,1,1]
	v_cvt_pk_bf16_f32 v190, v188, v189
	ds_write_b32 v191, v190 offset:12256
	s_waitcnt lgkmcnt(15)
	v_pk_fma_f32 v[184:185], v[66:67], v[188:189], v[168:169] op_sel:[1,1,0] op_sel_hi:[1,0,1] neg_lo:[1,0,0]
	v_pk_fma_f32 v[186:187], v[66:67], v[188:189], v[184:185] op_sel_hi:[0,1,1]
	v_mov_b32_e32 v102, v186
	v_mov_b32_e32 v103, v187
	v_cvt_pk_bf16_f32 v190, v186, v187
	ds_write_b32 v191, v190 offset:12528
	s_waitcnt vmcnt(0) lgkmcnt(0)
	ds_read_b128 v[4:7], v70 offset:8448
	ds_read_b128 v[94:97], v70 offset:8512
	s_waitcnt lgkmcnt(1)
	v_mfma_f32_16x16x32_bf16 v[4:7], v[4:7], v[24:27], 0
	s_waitcnt lgkmcnt(0)
	v_mfma_f32_16x16x32_bf16 v[4:7], v[94:97], v[20:23], v[4:7]
	ds_read_b128 v[94:97], v70 offset:8576
	s_waitcnt lgkmcnt(0)
	v_mfma_f32_16x16x32_bf16 v[4:7], v[94:97], v[16:19], v[4:7]
	ds_read_b128 v[94:97], v70 offset:8640
	s_waitcnt lgkmcnt(0)
	v_mfma_f32_16x16x32_bf16 v[4:7], v[94:97], v[12:15], v[4:7]
	v_mfma_f32_16x16x32_bf16 v[94:97], v[8:11], v[32:35], 0
	s_nop 7
	ds_write2_b32 v73, v94, v98 offset1:16
	ds_write2_b32 v73, v95, v99 offset0:132 offset1:148
	ds_write2_b32 v74, v96, v100 offset0:8 offset1:24
	ds_write2_b32 v74, v97, v101 offset0:140 offset1:156
	v_mfma_f32_16x16x32_bf16 v[94:97], v[8:11], v[40:43], 0
	v_mfma_f32_16x16x32_bf16 v[98:101], v[8:11], v[36:39], 0
	s_nop 7
	ds_write2_b32 v73, v94, v98 offset0:32 offset1:48
	ds_write2_b32 v73, v95, v99 offset0:164 offset1:180
	ds_write2_b32 v74, v96, v100 offset0:40 offset1:56
	ds_write2_b32 v74, v97, v101 offset0:172 offset1:188
	v_mfma_f32_16x16x32_bf16 v[94:97], v[8:11], v[48:51], 0
	v_mfma_f32_16x16x32_bf16 v[98:101], v[8:11], v[44:47], 0
	s_nop 7
	ds_write2_b32 v73, v94, v98 offset0:64 offset1:80
	ds_write2_b32 v73, v95, v99 offset0:196 offset1:212
	ds_write2_b32 v74, v96, v100 offset0:72 offset1:88
	ds_write2_b32 v74, v97, v101 offset0:204 offset1:220
	v_mfma_f32_16x16x32_bf16 v[94:97], v[8:11], v[56:59], 0
	v_mfma_f32_16x16x32_bf16 v[8:11], v[8:11], v[52:55], 0
	s_nop 7
	ds_write2_b32 v73, v94, v8 offset0:96 offset1:112
	ds_write2_b32 v73, v95, v9 offset0:228 offset1:244
	ds_write2_b32 v74, v96, v10 offset0:104 offset1:120
	ds_write2_b32 v74, v97, v11 offset0:236 offset1:252
	s_waitcnt vmcnt(0) lgkmcnt(0)
	ds_read2st64_b32 v[8:9], v75 offset1:1
	ds_read2_b32 v[140:141], v75 offset0:132 offset1:196
	ds_read2st64_b32 v[142:143], v71 offset0:4 offset1:5
	ds_read2st64_b32 v[144:145], v78 offset0:6 offset1:7
	ds_read2st64_b32 v[146:147], v79 offset0:8 offset1:9
	ds_read2st64_b32 v[148:149], v82 offset0:10 offset1:11
	ds_read2st64_b32 v[150:151], v83 offset0:12 offset1:13
	ds_read2st64_b32 v[152:153], v84 offset0:14 offset1:15
	ds_read2st64_b32 v[154:155], v85 offset0:16 offset1:17
	ds_read2st64_b32 v[156:157], v86 offset0:18 offset1:19
	ds_read2st64_b32 v[158:159], v87 offset0:20 offset1:21
	ds_read2st64_b32 v[160:161], v88 offset0:22 offset1:23
	ds_read2st64_b32 v[162:163], v89 offset0:24 offset1:25
	ds_read2st64_b32 v[164:165], v91 offset0:26 offset1:27
	ds_read2st64_b32 v[166:167], v92 offset0:28 offset1:29
	ds_read2st64_b32 v[168:169], v93 offset0:30 offset1:31
	v_mov_b32_e32 v186, v102
	v_mov_b32_e32 v187, v103
	v_mfma_f32_16x16x32_bf16 v[32:35], v[60:63], v[32:35], 0
	s_waitcnt lgkmcnt(15)
	v_pk_fma_f32 v[184:185], v[66:67], v[186:187], v[8:9] op_sel:[1,1,0] op_sel_hi:[1,0,1] neg_lo:[1,0,0]
	v_pk_fma_f32 v[188:189], v[66:67], v[186:187], v[184:185] op_sel_hi:[0,1,1]
	v_cvt_pk_bf16_f32 v190, v188, v189
	v_and_b32_e32 v191, 63, v207
	v_lshl_add_u32 v191, v191, 1, v72
	ds_write_b32 v191, v190 offset:8448
	s_waitcnt lgkmcnt(15)
	v_pk_fma_f32 v[184:185], v[66:67], v[188:189], v[140:141] op_sel:[1,1,0] op_sel_hi:[1,0,1] neg_lo:[1,0,0]
	v_pk_fma_f32 v[186:187], v[66:67], v[188:189], v[184:185] op_sel_hi:[0,1,1]
	v_cvt_pk_bf16_f32 v190, v186, v187
	ds_write_b32 v191, v190 offset:8720
	s_waitcnt lgkmcnt(15)
	v_pk_fma_f32 v[184:185], v[66:67], v[186:187], v[142:143] op_sel:[1,1,0] op_sel_hi:[1,0,1] neg_lo:[1,0,0]
	v_pk_fma_f32 v[188:189], v[66:67], v[186:187], v[184:185] op_sel_hi:[0,1,1]
	v_cvt_pk_bf16_f32 v190, v188, v189
	ds_write_b32 v191, v190 offset:8992
	s_waitcnt lgkmcnt(15)
	v_pk_fma_f32 v[184:185], v[66:67], v[188:189], v[144:145] op_sel:[1,1,0] op_sel_hi:[1,0,1] neg_lo:[1,0,0]
	v_pk_fma_f32 v[186:187], v[66:67], v[188:189], v[184:185] op_sel_hi:[0,1,1]
	v_cvt_pk_bf16_f32 v190, v186, v187
	ds_write_b32 v191, v190 offset:9264
	s_waitcnt lgkmcnt(15)
	v_pk_fma_f32 v[184:185], v[66:67], v[186:187], v[146:147] op_sel:[1,1,0] op_sel_hi:[1,0,1] neg_lo:[1,0,0]
	v_pk_fma_f32 v[188:189], v[66:67], v[186:187], v[184:185] op_sel_hi:[0,1,1]
	v_cvt_pk_bf16_f32 v190, v188, v189
	ds_write_b32 v191, v190 offset:9536
	s_waitcnt lgkmcnt(15)
	v_pk_fma_f32 v[184:185], v[66:67], v[188:189], v[148:149] op_sel:[1,1,0] op_sel_hi:[1,0,1] neg_lo:[1,0,0]
	v_pk_fma_f32 v[186:187], v[66:67], v[188:189], v[184:185] op_sel_hi:[0,1,1]
	v_cvt_pk_bf16_f32 v190, v186, v187
	ds_write_b32 v191, v190 offset:9808
	s_waitcnt lgkmcnt(15)
	v_pk_fma_f32 v[184:185], v[66:67], v[186:187], v[150:151] op_sel:[1,1,0] op_sel_hi:[1,0,1] neg_lo:[1,0,0]
	v_pk_fma_f32 v[188:189], v[66:67], v[186:187], v[184:185] op_sel_hi:[0,1,1]
	v_cvt_pk_bf16_f32 v190, v188, v189
	ds_write_b32 v191, v190 offset:10080
	s_waitcnt lgkmcnt(15)
	v_pk_fma_f32 v[184:185], v[66:67], v[188:189], v[152:153] op_sel:[1,1,0] op_sel_hi:[1,0,1] neg_lo:[1,0,0]
	v_pk_fma_f32 v[186:187], v[66:67], v[188:189], v[184:185] op_sel_hi:[0,1,1]
	v_cvt_pk_bf16_f32 v190, v186, v187
	ds_write_b32 v191, v190 offset:10352
	s_waitcnt lgkmcnt(15)
	v_pk_fma_f32 v[184:185], v[66:67], v[186:187], v[154:155] op_sel:[1,1,0] op_sel_hi:[1,0,1] neg_lo:[1,0,0]
	v_pk_fma_f32 v[188:189], v[66:67], v[186:187], v[184:185] op_sel_hi:[0,1,1]
	v_cvt_pk_bf16_f32 v190, v188, v189
	ds_write_b32 v191, v190 offset:10624
	s_waitcnt lgkmcnt(15)
	v_pk_fma_f32 v[184:185], v[66:67], v[188:189], v[156:157] op_sel:[1,1,0] op_sel_hi:[1,0,1] neg_lo:[1,0,0]
	v_pk_fma_f32 v[186:187], v[66:67], v[188:189], v[184:185] op_sel_hi:[0,1,1]
	v_cvt_pk_bf16_f32 v190, v186, v187
	ds_write_b32 v191, v190 offset:10896
	s_waitcnt lgkmcnt(15)
	v_pk_fma_f32 v[184:185], v[66:67], v[186:187], v[158:159] op_sel:[1,1,0] op_sel_hi:[1,0,1] neg_lo:[1,0,0]
	v_pk_fma_f32 v[188:189], v[66:67], v[186:187], v[184:185] op_sel_hi:[0,1,1]
	v_cvt_pk_bf16_f32 v190, v188, v189
	ds_write_b32 v191, v190 offset:11168
	s_waitcnt lgkmcnt(15)
	v_pk_fma_f32 v[184:185], v[66:67], v[188:189], v[160:161] op_sel:[1,1,0] op_sel_hi:[1,0,1] neg_lo:[1,0,0]
	v_pk_fma_f32 v[186:187], v[66:67], v[188:189], v[184:185] op_sel_hi:[0,1,1]
	v_cvt_pk_bf16_f32 v190, v186, v187
	ds_write_b32 v191, v190 offset:11440
	s_waitcnt lgkmcnt(15)
	v_pk_fma_f32 v[184:185], v[66:67], v[186:187], v[162:163] op_sel:[1,1,0] op_sel_hi:[1,0,1] neg_lo:[1,0,0]
	v_pk_fma_f32 v[188:189], v[66:67], v[186:187], v[184:185] op_sel_hi:[0,1,1]
	v_cvt_pk_bf16_f32 v190, v188, v189
	ds_write_b32 v191, v190 offset:11712
	s_waitcnt lgkmcnt(15)
	v_pk_fma_f32 v[184:185], v[66:67], v[188:189], v[164:165] op_sel:[1,1,0] op_sel_hi:[1,0,1] neg_lo:[1,0,0]
	v_pk_fma_f32 v[186:187], v[66:67], v[188:189], v[184:185] op_sel_hi:[0,1,1]
	v_cvt_pk_bf16_f32 v190, v186, v187
	ds_write_b32 v191, v190 offset:11984
	s_waitcnt lgkmcnt(15)
	v_pk_fma_f32 v[184:185], v[66:67], v[186:187], v[166:167] op_sel:[1,1,0] op_sel_hi:[1,0,1] neg_lo:[1,0,0]
	v_pk_fma_f32 v[188:189], v[66:67], v[186:187], v[184:185] op_sel_hi:[0,1,1]
	v_cvt_pk_bf16_f32 v190, v188, v189
	ds_write_b32 v191, v190 offset:12256
	s_waitcnt lgkmcnt(15)
	v_pk_fma_f32 v[184:185], v[66:67], v[188:189], v[168:169] op_sel:[1,1,0] op_sel_hi:[1,0,1] neg_lo:[1,0,0]
	v_pk_fma_f32 v[186:187], v[66:67], v[188:189], v[184:185] op_sel_hi:[0,1,1]
	v_mov_b32_e32 v98, v186
	v_mov_b32_e32 v99, v187
	v_cvt_pk_bf16_f32 v190, v186, v187
	ds_write_b32 v191, v190 offset:12528
	s_waitcnt vmcnt(0) lgkmcnt(0)
	ds_read_b128 v[8:11], v70 offset:8448
	ds_read_b128 v[94:97], v70 offset:8512
	s_waitcnt lgkmcnt(1)
	v_mfma_f32_16x16x32_bf16 v[8:11], v[8:11], v[24:27], 0
	s_waitcnt lgkmcnt(0)
	v_mfma_f32_16x16x32_bf16 v[8:11], v[94:97], v[20:23], v[8:11]
	ds_read_b128 v[94:97], v70 offset:8576
	s_waitcnt lgkmcnt(0)
	v_mfma_f32_16x16x32_bf16 v[8:11], v[94:97], v[16:19], v[8:11]
	ds_read_b128 v[94:97], v70 offset:8640
	ds_write2_b32 v73, v32, v28 offset1:16
	ds_write2_b32 v73, v33, v29 offset0:132 offset1:148
	ds_write2_b32 v74, v34, v30 offset0:8 offset1:24
	ds_write2_b32 v74, v35, v31 offset0:140 offset1:156
	v_mfma_f32_16x16x32_bf16 v[28:31], v[60:63], v[40:43], 0
	v_mov_b32_e32 v40, 0
	v_mov_b32_e32 v41, 0
	v_mov_b32_e32 v42, 0
	v_mfma_f32_16x16x32_bf16 v[32:35], v[60:63], v[36:39], 0
	s_nop 7
	ds_write2_b32 v73, v28, v32 offset0:32 offset1:48
	ds_write2_b32 v73, v29, v33 offset0:164 offset1:180
	ds_write2_b32 v74, v30, v34 offset0:40 offset1:56
	ds_write2_b32 v74, v31, v35 offset0:172 offset1:188
	v_mfma_f32_16x16x32_bf16 v[28:31], v[60:63], v[48:51], 0
	v_mov_b32_e32 v36, 0
	v_mov_b32_e32 v43, 0
	v_mfma_f32_16x16x32_bf16 v[32:35], v[60:63], v[44:47], 0
	s_nop 7
	ds_write2_b32 v73, v28, v32 offset0:64 offset1:80
	ds_write2_b32 v73, v29, v33 offset0:196 offset1:212
	ds_write2_b32 v74, v30, v34 offset0:72 offset1:88
	ds_write2_b32 v74, v31, v35 offset0:204 offset1:220
	v_mfma_f32_16x16x32_bf16 v[28:31], v[60:63], v[56:59], 0
	v_mfma_f32_16x16x32_bf16 v[32:35], v[60:63], v[52:55], 0
	s_nop 7
	ds_write2_b32 v73, v28, v32 offset0:96 offset1:112
	ds_write2_b32 v73, v29, v33 offset0:228 offset1:244
	ds_write2_b32 v74, v30, v34 offset0:104 offset1:120
	ds_write2_b32 v74, v31, v35 offset0:236 offset1:252
	s_waitcnt vmcnt(0) lgkmcnt(0)
	ds_read2st64_b32 v[28:29], v75 offset1:1
	ds_read2_b32 v[140:141], v75 offset0:132 offset1:196
	ds_read2st64_b32 v[142:143], v71 offset0:4 offset1:5
	ds_read2st64_b32 v[144:145], v78 offset0:6 offset1:7
	ds_read2st64_b32 v[146:147], v79 offset0:8 offset1:9
	ds_read2st64_b32 v[148:149], v82 offset0:10 offset1:11
	ds_read2st64_b32 v[150:151], v83 offset0:12 offset1:13
	ds_read2st64_b32 v[152:153], v84 offset0:14 offset1:15
	ds_read2st64_b32 v[154:155], v85 offset0:16 offset1:17
	ds_read2st64_b32 v[156:157], v86 offset0:18 offset1:19
	ds_read2st64_b32 v[158:159], v87 offset0:20 offset1:21
	ds_read2st64_b32 v[160:161], v88 offset0:22 offset1:23
	ds_read2st64_b32 v[162:163], v89 offset0:24 offset1:25
	ds_read2st64_b32 v[164:165], v91 offset0:26 offset1:27
	ds_read2st64_b32 v[166:167], v92 offset0:28 offset1:29
	ds_read2st64_b32 v[168:169], v93 offset0:30 offset1:31
	v_mov_b32_e32 v186, v98
	v_mov_b32_e32 v187, v99
	s_waitcnt lgkmcnt(15)
	v_mfma_f32_16x16x32_bf16 v[8:11], v[94:97], v[12:15], v[8:11]
	v_pk_fma_f32 v[184:185], v[66:67], v[186:187], v[28:29] op_sel:[1,1,0] op_sel_hi:[1,0,1] neg_lo:[1,0,0]
	v_pk_fma_f32 v[188:189], v[66:67], v[186:187], v[184:185] op_sel_hi:[0,1,1]
	v_cvt_pk_bf16_f32 v190, v188, v189
	v_and_b32_e32 v191, 63, v207
	v_lshl_add_u32 v191, v191, 1, v72
	ds_write_b32 v191, v190 offset:8448
	s_waitcnt lgkmcnt(15)
	v_pk_fma_f32 v[184:185], v[66:67], v[188:189], v[140:141] op_sel:[1,1,0] op_sel_hi:[1,0,1] neg_lo:[1,0,0]
	v_pk_fma_f32 v[186:187], v[66:67], v[188:189], v[184:185] op_sel_hi:[0,1,1]
	v_cvt_pk_bf16_f32 v190, v186, v187
	ds_write_b32 v191, v190 offset:8720
	s_waitcnt lgkmcnt(15)
	v_pk_fma_f32 v[184:185], v[66:67], v[186:187], v[142:143] op_sel:[1,1,0] op_sel_hi:[1,0,1] neg_lo:[1,0,0]
	v_pk_fma_f32 v[188:189], v[66:67], v[186:187], v[184:185] op_sel_hi:[0,1,1]
	v_cvt_pk_bf16_f32 v190, v188, v189
	ds_write_b32 v191, v190 offset:8992
	s_waitcnt lgkmcnt(15)
	v_pk_fma_f32 v[184:185], v[66:67], v[188:189], v[144:145] op_sel:[1,1,0] op_sel_hi:[1,0,1] neg_lo:[1,0,0]
	v_pk_fma_f32 v[186:187], v[66:67], v[188:189], v[184:185] op_sel_hi:[0,1,1]
	v_cvt_pk_bf16_f32 v190, v186, v187
	ds_write_b32 v191, v190 offset:9264
	s_waitcnt lgkmcnt(15)
	v_pk_fma_f32 v[184:185], v[66:67], v[186:187], v[146:147] op_sel:[1,1,0] op_sel_hi:[1,0,1] neg_lo:[1,0,0]
	v_pk_fma_f32 v[188:189], v[66:67], v[186:187], v[184:185] op_sel_hi:[0,1,1]
	v_cvt_pk_bf16_f32 v190, v188, v189
	ds_write_b32 v191, v190 offset:9536
	s_waitcnt lgkmcnt(15)
	v_pk_fma_f32 v[184:185], v[66:67], v[188:189], v[148:149] op_sel:[1,1,0] op_sel_hi:[1,0,1] neg_lo:[1,0,0]
	v_pk_fma_f32 v[186:187], v[66:67], v[188:189], v[184:185] op_sel_hi:[0,1,1]
	v_cvt_pk_bf16_f32 v190, v186, v187
	ds_write_b32 v191, v190 offset:9808
	s_waitcnt lgkmcnt(15)
	v_pk_fma_f32 v[184:185], v[66:67], v[186:187], v[150:151] op_sel:[1,1,0] op_sel_hi:[1,0,1] neg_lo:[1,0,0]
	v_pk_fma_f32 v[188:189], v[66:67], v[186:187], v[184:185] op_sel_hi:[0,1,1]
	v_cvt_pk_bf16_f32 v190, v188, v189
	ds_write_b32 v191, v190 offset:10080
	s_waitcnt lgkmcnt(15)
	v_pk_fma_f32 v[184:185], v[66:67], v[188:189], v[152:153] op_sel:[1,1,0] op_sel_hi:[1,0,1] neg_lo:[1,0,0]
	v_pk_fma_f32 v[186:187], v[66:67], v[188:189], v[184:185] op_sel_hi:[0,1,1]
	v_cvt_pk_bf16_f32 v190, v186, v187
	ds_write_b32 v191, v190 offset:10352
	s_waitcnt lgkmcnt(15)
	v_pk_fma_f32 v[184:185], v[66:67], v[186:187], v[154:155] op_sel:[1,1,0] op_sel_hi:[1,0,1] neg_lo:[1,0,0]
	v_pk_fma_f32 v[188:189], v[66:67], v[186:187], v[184:185] op_sel_hi:[0,1,1]
	v_cvt_pk_bf16_f32 v190, v188, v189
	ds_write_b32 v191, v190 offset:10624
	s_waitcnt lgkmcnt(15)
	v_pk_fma_f32 v[184:185], v[66:67], v[188:189], v[156:157] op_sel:[1,1,0] op_sel_hi:[1,0,1] neg_lo:[1,0,0]
	v_pk_fma_f32 v[186:187], v[66:67], v[188:189], v[184:185] op_sel_hi:[0,1,1]
	v_cvt_pk_bf16_f32 v190, v186, v187
	ds_write_b32 v191, v190 offset:10896
	s_waitcnt lgkmcnt(15)
	v_pk_fma_f32 v[184:185], v[66:67], v[186:187], v[158:159] op_sel:[1,1,0] op_sel_hi:[1,0,1] neg_lo:[1,0,0]
	v_pk_fma_f32 v[188:189], v[66:67], v[186:187], v[184:185] op_sel_hi:[0,1,1]
	v_cvt_pk_bf16_f32 v190, v188, v189
	ds_write_b32 v191, v190 offset:11168
	s_waitcnt lgkmcnt(15)
	v_pk_fma_f32 v[184:185], v[66:67], v[188:189], v[160:161] op_sel:[1,1,0] op_sel_hi:[1,0,1] neg_lo:[1,0,0]
	v_pk_fma_f32 v[186:187], v[66:67], v[188:189], v[184:185] op_sel_hi:[0,1,1]
	v_cvt_pk_bf16_f32 v190, v186, v187
	ds_write_b32 v191, v190 offset:11440
	s_waitcnt lgkmcnt(15)
	v_pk_fma_f32 v[184:185], v[66:67], v[186:187], v[162:163] op_sel:[1,1,0] op_sel_hi:[1,0,1] neg_lo:[1,0,0]
	v_pk_fma_f32 v[188:189], v[66:67], v[186:187], v[184:185] op_sel_hi:[0,1,1]
	v_cvt_pk_bf16_f32 v190, v188, v189
	ds_write_b32 v191, v190 offset:11712
	s_waitcnt lgkmcnt(15)
	v_pk_fma_f32 v[184:185], v[66:67], v[188:189], v[164:165] op_sel:[1,1,0] op_sel_hi:[1,0,1] neg_lo:[1,0,0]
	v_pk_fma_f32 v[186:187], v[66:67], v[188:189], v[184:185] op_sel_hi:[0,1,1]
	v_cvt_pk_bf16_f32 v190, v186, v187
	ds_write_b32 v191, v190 offset:11984
	s_waitcnt lgkmcnt(15)
	v_pk_fma_f32 v[184:185], v[66:67], v[186:187], v[166:167] op_sel:[1,1,0] op_sel_hi:[1,0,1] neg_lo:[1,0,0]
	v_pk_fma_f32 v[188:189], v[66:67], v[186:187], v[184:185] op_sel_hi:[0,1,1]
	v_cvt_pk_bf16_f32 v190, v188, v189
	ds_write_b32 v191, v190 offset:12256
	s_waitcnt lgkmcnt(15)
	v_pk_fma_f32 v[184:185], v[66:67], v[188:189], v[168:169] op_sel:[1,1,0] op_sel_hi:[1,0,1] neg_lo:[1,0,0]
	v_pk_fma_f32 v[186:187], v[66:67], v[188:189], v[184:185] op_sel_hi:[0,1,1]
	v_mov_b32_e32 v28, v186
	v_mov_b32_e32 v29, v187
	v_cvt_pk_bf16_f32 v190, v186, v187
	ds_write_b32 v191, v190 offset:12528
	s_waitcnt vmcnt(0) lgkmcnt(0)
	ds_read_b128 v[28:31], v70 offset:8448
	s_waitcnt lgkmcnt(0)
	v_mfma_f32_16x16x32_bf16 v[24:27], v[28:31], v[24:27], 0
	ds_read_b128 v[28:31], v70 offset:8512
	s_add_u32 s0, s0, s1
	s_addc_u32 s1, s2, 0
	s_waitcnt lgkmcnt(0)
	v_mfma_f32_16x16x32_bf16 v[20:23], v[28:31], v[20:23], v[24:27]
	s_nop 2
	ds_read_b128 v[24:27], v70 offset:8576
	s_lshl_b64 s[0:1], s[0:1], 14
	s_waitcnt lgkmcnt(0)
	v_mfma_f32_16x16x32_bf16 v[16:19], v[24:27], v[16:19], v[20:23]
	s_nop 2
	ds_read_b128 v[20:23], v70 offset:8640
	s_waitcnt lgkmcnt(0)
	v_mfma_f32_16x16x32_bf16 v[12:15], v[20:23], v[12:15], v[16:19]
	s_nop 2
	v_lshl_add_u64 v[16:17], v[64:65], 0, s[0:1]
	v_mov_b32_e32 v20, v207
	global_load_dwordx2 v[84:85], v[16:17], off
	v_add_u32_e32 v16, s90, v77
	v_and_b32_e32 v91, 63, v20
	v_or_b32_e32 v16, v91, v16
	v_ashrrev_i32_e32 v17, 31, v16
	v_lshl_add_u64 v[16:17], v[16:17], 3, s[60:61]
	global_load_dwordx2 v[82:83], v[16:17], off
	v_add_u32_e32 v16, s91, v76
	v_ashrrev_i32_e32 v17, 31, v16
	v_and_b32_e32 v92, 15, v20
	v_lshlrev_b64 v[16:17], 12, v[16:17]
	v_lshl_add_u64 v[18:19], s[62:63], 0, v[16:17]
	v_lshlrev_b32_e32 v21, 4, v92
	v_and_b32_e32 v128, 48, v20
	v_cmp_gt_u32_e64 s[42:43], 32, v91
	v_lshl_add_u64 v[18:19], v[18:19], 0, v[128:129]
	v_lshlrev_b32_e32 v128, 1, v21
	s_and_saveexec_b64 s[0:1], s[42:43]
	s_cbranch_execz .LBB0_1789
	v_lshl_add_u64 v[22:23], v[18:19], 0, v[128:129]
	global_load_dwordx4 v[40:43], v[22:23], off

.LBB0_1811:
	s_or_b64 exec, exec, s[0:1]
	s_waitcnt vmcnt(0) lgkmcnt(0)
	v_mov_b32_e32 v158, 0x5040100
	v_mov_b32_e32 v159, 0x7060302
	v_perm_b32 v32, v142, v140, v158
	v_perm_b32 v33, v142, v140, v159
	v_perm_b32 v34, v143, v141, v158
	v_perm_b32 v35, v143, v141, v159
	v_perm_b32 v28, v146, v144, v158
	v_perm_b32 v29, v146, v144, v159
	v_perm_b32 v30, v147, v145, v158
	v_perm_b32 v31, v147, v145, v159
	v_perm_b32 v24, v150, v148, v158
	v_perm_b32 v25, v150, v148, v159
	v_perm_b32 v26, v151, v149, v158
	v_perm_b32 v27, v151, v149, v159
	v_perm_b32 v20, v154, v152, v158
	v_perm_b32 v21, v154, v152, v159
	v_perm_b32 v22, v155, v153, v158
	v_perm_b32 v23, v155, v153, v159
	v_mfma_f32_16x16x32_bf16 v[94:97], v[16:19], v[40:43], 0
	v_mul_u32_u24_e32 v86, 0x210, v93
	v_lshlrev_b32_e32 v87, 2, v92
	v_lshlrev_b32_e32 v86, 2, v86
	v_mfma_f32_16x16x32_bf16 v[98:101], v[16:19], v[36:39], 0
	v_add3_u32 v88, v81, v87, v86
	v_add_u32_e32 v89, 0x400, v88
	v_mul_u32_u24_e32 v103, 0x110, v92
	s_nop 4
	ds_write2_b32 v88, v94, v98 offset1:16
	ds_write2_b32 v88, v95, v99 offset0:132 offset1:148
	ds_write2_b32 v89, v96, v100 offset0:8 offset1:24
	ds_write2_b32 v89, v97, v101 offset0:140 offset1:156
	v_mfma_f32_16x16x32_bf16 v[92:95], v[16:19], v[48:51], 0
	v_lshl_add_u32 v87, v91, 2, v81
	v_add3_u32 v81, v81, v128, v103
	v_pk_add_f32 v[0:1], v[0:1], 0 op_sel_hi:[1,0]
	v_mfma_f32_16x16x32_bf16 v[96:99], v[16:19], v[44:47], 0
	s_nop 7
	ds_write2_b32 v88, v92, v96 offset0:32 offset1:48
	ds_write2_b32 v88, v93, v97 offset0:164 offset1:180
	ds_write2_b32 v89, v94, v98 offset0:40 offset1:56
	ds_write2_b32 v89, v95, v99 offset0:172 offset1:188
	v_mfma_f32_16x16x32_bf16 v[92:95], v[16:19], v[56:59], 0
	v_readlane_b32 s68, v251, 41
	v_readlane_b32 s76, v251, 49
	v_readlane_b32 s77, v251, 50
	v_mfma_f32_16x16x32_bf16 v[96:99], v[16:19], v[52:55], 0
	s_nop 7
	ds_write2_b32 v88, v92, v96 offset0:64 offset1:80
	ds_write2_b32 v88, v93, v97 offset0:196 offset1:212
	ds_write2_b32 v89, v94, v98 offset0:72 offset1:88
	ds_write2_b32 v89, v95, v99 offset0:204 offset1:220
	v_mfma_f32_16x16x32_bf16 v[92:95], v[16:19], v[64:67], 0
	s_mov_b32 s10, 0x3f200000
	v_readlane_b32 s69, v251, 42
	v_readlane_b32 s70, v251, 43
	v_mfma_f32_16x16x32_bf16 v[16:19], v[16:19], v[60:63], 0
	s_nop 7
	ds_write2_b32 v88, v92, v16 offset0:96 offset1:112
	ds_write2_b32 v88, v93, v17 offset0:228 offset1:244
	ds_write2_b32 v89, v94, v18 offset0:104 offset1:120
	ds_write2_b32 v89, v95, v19 offset0:236 offset1:252
	v_lshlrev_b32_e32 v16, 1, v91
	v_add_u32_e32 v91, 0xf0, v87
	s_waitcnt vmcnt(0) lgkmcnt(0)
	v_sub_u32_e32 v86, v87, v16
	ds_read2st64_b32 v[16:17], v91 offset0:30 offset1:31
	v_add_u32_e32 v140, 0xe0, v87
	ds_read2st64_b32 v[142:143], v140 offset0:28 offset1:29
	v_add_u32_e32 v141, 0xd0, v87
	ds_read2st64_b32 v[144:145], v141 offset0:26 offset1:27
	v_add_u32_e32 v146, 0xc0, v87
	ds_read2st64_b32 v[148:149], v146 offset0:24 offset1:25
	v_add_u32_e32 v147, 0xb0, v87
	ds_read2st64_b32 v[150:151], v147 offset0:22 offset1:23
	v_add_u32_e32 v152, 0xa0, v87
	ds_read2st64_b32 v[154:155], v152 offset0:20 offset1:21
	v_add_u32_e32 v153, 0x90, v87
	ds_read2st64_b32 v[156:157], v153 offset0:18 offset1:19
	v_add_u32_e32 v158, 0x80, v87
	ds_read2st64_b32 v[160:161], v158 offset0:16 offset1:17
	v_add_u32_e32 v159, 0x70, v87
	ds_read2st64_b32 v[162:163], v159 offset0:14 offset1:15
	v_add_u32_e32 v164, 0x60, v87
	ds_read2st64_b32 v[166:167], v164 offset0:12 offset1:13
	v_add_u32_e32 v165, 0x50, v87
	ds_read2st64_b32 v[168:169], v165 offset0:10 offset1:11
	v_add_u32_e32 v170, 64, v87
	ds_read2st64_b32 v[172:173], v170 offset0:8 offset1:9
	v_add_u32_e32 v171, 48, v87
	ds_read2st64_b32 v[174:175], v171 offset0:6 offset1:7
	v_add_u32_e32 v176, 32, v87
	ds_read2st64_b32 v[178:179], v176 offset0:4 offset1:5
	ds_read2_b32 v[180:181], v87 offset0:132 offset1:196
	ds_read2st64_b32 v[182:183], v87 offset1:1
	v_mov_b32_e32 v186, v84
	v_mov_b32_e32 v187, v85
	v_mfma_f32_16x16x32_bf16 v[108:111], v[72:75], v[36:39], 0
	v_readlane_b32 s71, v251, 44
	s_waitcnt lgkmcnt(15)
	v_pk_fma_f32 v[184:185], v[82:83], v[186:187], v[16:17] op_sel:[1,1,0] op_sel_hi:[1,0,1] neg_lo:[1,0,0]
	v_pk_fma_f32 v[188:189], v[82:83], v[186:187], v[184:185] op_sel_hi:[0,1,1]
	v_cvt_pk_bf16_f32 v190, v188, v189
	v_and_b32_e32 v191, 63, v207
	v_lshl_add_u32 v191, v191, 1, v86
	ds_write_b32 v191, v190 offset:12528
	v_add_u32_e32 v84, 0xe0, v87
	v_readlane_b32 s72, v251, 45
	v_readlane_b32 s73, v251, 46
	s_waitcnt lgkmcnt(15)
	v_pk_fma_f32 v[184:185], v[82:83], v[188:189], v[142:143] op_sel:[1,1,0] op_sel_hi:[1,0,1] neg_lo:[1,0,0]
	v_pk_fma_f32 v[186:187], v[82:83], v[188:189], v[184:185] op_sel_hi:[0,1,1]
	v_cvt_pk_bf16_f32 v190, v186, v187
	ds_write_b32 v191, v190 offset:12256
	v_add_u32_e32 v85, 0xd0, v87
	v_readlane_b32 s74, v251, 47
	v_readlane_b32 s75, v251, 48
	s_waitcnt lgkmcnt(15)
	v_pk_fma_f32 v[184:185], v[82:83], v[186:187], v[144:145] op_sel:[1,1,0] op_sel_hi:[1,0,1] neg_lo:[1,0,0]
	v_pk_fma_f32 v[188:189], v[82:83], v[186:187], v[184:185] op_sel_hi:[0,1,1]
	v_cvt_pk_bf16_f32 v190, v188, v189
	ds_write_b32 v191, v190 offset:11984
	v_add_u32_e32 v92, 0xc0, v87
	v_readlane_b32 s78, v251, 51
	v_readlane_b32 s79, v251, 52
	s_waitcnt lgkmcnt(15)
	v_pk_fma_f32 v[184:185], v[82:83], v[188:189], v[148:149] op_sel:[1,1,0] op_sel_hi:[1,0,1] neg_lo:[1,0,0]
	v_pk_fma_f32 v[186:187], v[82:83], v[188:189], v[184:185] op_sel_hi:[0,1,1]
	v_cvt_pk_bf16_f32 v190, v186, v187
	ds_write_b32 v191, v190 offset:11712
	v_add_u32_e32 v93, 0xb0, v87
	v_readlane_b32 s80, v251, 53
	v_readlane_b32 s81, v251, 54
	s_waitcnt lgkmcnt(15)
	v_pk_fma_f32 v[184:185], v[82:83], v[186:187], v[150:151] op_sel:[1,1,0] op_sel_hi:[1,0,1] neg_lo:[1,0,0]
	v_pk_fma_f32 v[188:189], v[82:83], v[186:187], v[184:185] op_sel_hi:[0,1,1]
	v_cvt_pk_bf16_f32 v190, v188, v189
	ds_write_b32 v191, v190 offset:11440
	v_add_u32_e32 v94, 0xa0, v87
	v_readlane_b32 s82, v251, 55
	v_readlane_b32 s83, v251, 56
	s_waitcnt lgkmcnt(15)
	v_pk_fma_f32 v[184:185], v[82:83], v[188:189], v[154:155] op_sel:[1,1,0] op_sel_hi:[1,0,1] neg_lo:[1,0,0]
	v_pk_fma_f32 v[186:187], v[82:83], v[188:189], v[184:185] op_sel_hi:[0,1,1]
	v_cvt_pk_bf16_f32 v190, v186, v187
	ds_write_b32 v191, v190 offset:11168
	v_add_u32_e32 v95, 0x90, v87
	s_waitcnt lgkmcnt(15)
	v_pk_fma_f32 v[184:185], v[82:83], v[186:187], v[156:157] op_sel:[1,1,0] op_sel_hi:[1,0,1] neg_lo:[1,0,0]
	v_pk_fma_f32 v[188:189], v[82:83], v[186:187], v[184:185] op_sel_hi:[0,1,1]
	v_cvt_pk_bf16_f32 v190, v188, v189
	ds_write_b32 v191, v190 offset:10896
	v_add_u32_e32 v96, 0x80, v87
	s_waitcnt lgkmcnt(15)
	v_pk_fma_f32 v[184:185], v[82:83], v[188:189], v[160:161] op_sel:[1,1,0] op_sel_hi:[1,0,1] neg_lo:[1,0,0]
	v_pk_fma_f32 v[186:187], v[82:83], v[188:189], v[184:185] op_sel_hi:[0,1,1]
	v_cvt_pk_bf16_f32 v190, v186, v187
	ds_write_b32 v191, v190 offset:10624
	v_add_u32_e32 v97, 0x70, v87
	s_waitcnt lgkmcnt(15)
	v_pk_fma_f32 v[184:185], v[82:83], v[186:187], v[162:163] op_sel:[1,1,0] op_sel_hi:[1,0,1] neg_lo:[1,0,0]
	v_pk_fma_f32 v[188:189], v[82:83], v[186:187], v[184:185] op_sel_hi:[0,1,1]
	v_cvt_pk_bf16_f32 v190, v188, v189
	ds_write_b32 v191, v190 offset:10352
	v_add_u32_e32 v98, 0x60, v87
	s_waitcnt lgkmcnt(15)
	v_pk_fma_f32 v[184:185], v[82:83], v[188:189], v[166:167] op_sel:[1,1,0] op_sel_hi:[1,0,1] neg_lo:[1,0,0]
	v_pk_fma_f32 v[186:187], v[82:83], v[188:189], v[184:185] op_sel_hi:[0,1,1]
	v_cvt_pk_bf16_f32 v190, v186, v187
	ds_write_b32 v191, v190 offset:10080
	v_add_u32_e32 v99, 0x50, v87
	s_waitcnt lgkmcnt(15)
	v_pk_fma_f32 v[184:185], v[82:83], v[186:187], v[168:169] op_sel:[1,1,0] op_sel_hi:[1,0,1] neg_lo:[1,0,0]
	v_pk_fma_f32 v[188:189], v[82:83], v[186:187], v[184:185] op_sel_hi:[0,1,1]
	v_cvt_pk_bf16_f32 v190, v188, v189
	ds_write_b32 v191, v190 offset:9808
	v_add_u32_e32 v100, 64, v87
	s_waitcnt lgkmcnt(15)
	v_pk_fma_f32 v[184:185], v[82:83], v[188:189], v[172:173] op_sel:[1,1,0] op_sel_hi:[1,0,1] neg_lo:[1,0,0]
	v_pk_fma_f32 v[186:187], v[82:83], v[188:189], v[184:185] op_sel_hi:[0,1,1]
	v_cvt_pk_bf16_f32 v190, v186, v187
	ds_write_b32 v191, v190 offset:9536
	v_add_u32_e32 v101, 48, v87
	s_waitcnt lgkmcnt(15)
	v_pk_fma_f32 v[184:185], v[82:83], v[186:187], v[174:175] op_sel:[1,1,0] op_sel_hi:[1,0,1] neg_lo:[1,0,0]
	v_pk_fma_f32 v[188:189], v[82:83], v[186:187], v[184:185] op_sel_hi:[0,1,1]
	v_cvt_pk_bf16_f32 v190, v188, v189
	ds_write_b32 v191, v190 offset:9264
	v_add_u32_e32 v102, 32, v87
	s_waitcnt lgkmcnt(15)
	v_pk_fma_f32 v[184:185], v[82:83], v[188:189], v[178:179] op_sel:[1,1,0] op_sel_hi:[1,0,1] neg_lo:[1,0,0]
	v_pk_fma_f32 v[186:187], v[82:83], v[188:189], v[184:185] op_sel_hi:[0,1,1]
	v_cvt_pk_bf16_f32 v190, v186, v187
	ds_write_b32 v191, v190 offset:8992
	s_waitcnt lgkmcnt(15)
	v_pk_fma_f32 v[184:185], v[82:83], v[186:187], v[180:181] op_sel:[1,1,0] op_sel_hi:[1,0,1] neg_lo:[1,0,0]
	v_pk_fma_f32 v[188:189], v[82:83], v[186:187], v[184:185] op_sel_hi:[0,1,1]
	v_cvt_pk_bf16_f32 v190, v188, v189
	ds_write_b32 v191, v190 offset:8720
	s_waitcnt lgkmcnt(15)
	v_pk_fma_f32 v[184:185], v[82:83], v[188:189], v[182:183] op_sel:[1,1,0] op_sel_hi:[1,0,1] neg_lo:[1,0,0]
	v_pk_fma_f32 v[186:187], v[82:83], v[188:189], v[184:185] op_sel_hi:[0,1,1]
	v_mov_b32_e32 v112, v186
	v_mov_b32_e32 v113, v187
	v_cvt_pk_bf16_f32 v190, v186, v187
	ds_write_b32 v191, v190 offset:8448
	s_waitcnt vmcnt(0) lgkmcnt(0)
	ds_read_b128 v[16:19], v81 offset:8448
	ds_read_b128 v[104:107], v81 offset:8512
	s_waitcnt lgkmcnt(1)
	v_mfma_f32_16x16x32_bf16 v[16:19], v[16:19], v[32:35], 0
	s_waitcnt lgkmcnt(0)
	v_mfma_f32_16x16x32_bf16 v[16:19], v[104:107], v[28:31], v[16:19]
	ds_read_b128 v[104:107], v81 offset:8576
	s_waitcnt lgkmcnt(0)
	v_mfma_f32_16x16x32_bf16 v[16:19], v[104:107], v[24:27], v[16:19]
	ds_read_b128 v[104:107], v81 offset:8640
	s_waitcnt lgkmcnt(0)
	v_mfma_f32_16x16x32_bf16 v[16:19], v[104:107], v[20:23], v[16:19]
	v_mfma_f32_16x16x32_bf16 v[104:107], v[72:75], v[40:43], 0
	s_nop 7
	ds_write2_b32 v88, v104, v108 offset1:16
	ds_write2_b32 v88, v105, v109 offset0:132 offset1:148
	ds_write2_b32 v89, v106, v110 offset0:8 offset1:24
	ds_write2_b32 v89, v107, v111 offset0:140 offset1:156
	v_mfma_f32_16x16x32_bf16 v[104:107], v[72:75], v[48:51], 0
	v_mfma_f32_16x16x32_bf16 v[108:111], v[72:75], v[44:47], 0
	s_nop 7
	ds_write2_b32 v88, v104, v108 offset0:32 offset1:48
	ds_write2_b32 v88, v105, v109 offset0:164 offset1:180
	ds_write2_b32 v89, v106, v110 offset0:40 offset1:56
	ds_write2_b32 v89, v107, v111 offset0:172 offset1:188
	v_mfma_f32_16x16x32_bf16 v[104:107], v[72:75], v[56:59], 0
	v_mfma_f32_16x16x32_bf16 v[108:111], v[72:75], v[52:55], 0
	s_nop 7
	ds_write2_b32 v88, v104, v108 offset0:64 offset1:80
	ds_write2_b32 v88, v105, v109 offset0:196 offset1:212
	ds_write2_b32 v89, v106, v110 offset0:72 offset1:88
	ds_write2_b32 v89, v107, v111 offset0:204 offset1:220
	v_mfma_f32_16x16x32_bf16 v[104:107], v[72:75], v[64:67], 0
	v_mfma_f32_16x16x32_bf16 v[72:75], v[72:75], v[60:63], 0
	s_nop 7
	ds_write2_b32 v88, v104, v72 offset0:96 offset1:112
	ds_write2_b32 v88, v105, v73 offset0:228 offset1:244
	ds_write2_b32 v89, v106, v74 offset0:104 offset1:120
	ds_write2_b32 v89, v107, v75 offset0:236 offset1:252
	s_waitcnt vmcnt(0) lgkmcnt(0)
	ds_read2st64_b32 v[72:73], v91 offset0:30 offset1:31
	ds_read2st64_b32 v[140:141], v84 offset0:28 offset1:29
	ds_read2st64_b32 v[142:143], v85 offset0:26 offset1:27
	ds_read2st64_b32 v[144:145], v92 offset0:24 offset1:25
	ds_read2st64_b32 v[146:147], v93 offset0:22 offset1:23
	ds_read2st64_b32 v[148:149], v94 offset0:20 offset1:21
	ds_read2st64_b32 v[150:151], v95 offset0:18 offset1:19
	ds_read2st64_b32 v[152:153], v96 offset0:16 offset1:17
	ds_read2st64_b32 v[154:155], v97 offset0:14 offset1:15
	ds_read2st64_b32 v[156:157], v98 offset0:12 offset1:13
	ds_read2st64_b32 v[158:159], v99 offset0:10 offset1:11
	ds_read2st64_b32 v[160:161], v100 offset0:8 offset1:9
	ds_read2st64_b32 v[162:163], v101 offset0:6 offset1:7
	ds_read2st64_b32 v[164:165], v102 offset0:4 offset1:5
	ds_read2_b32 v[166:167], v87 offset0:132 offset1:196
	ds_read2st64_b32 v[168:169], v87 offset1:1
	v_mov_b32_e32 v186, v112
	v_mov_b32_e32 v187, v113
	v_mfma_f32_16x16x32_bf16 v[108:111], v[76:79], v[36:39], 0
	s_waitcnt lgkmcnt(15)
	v_pk_fma_f32 v[184:185], v[82:83], v[186:187], v[72:73] op_sel:[1,1,0] op_sel_hi:[1,0,1] neg_lo:[1,0,0]
	v_pk_fma_f32 v[188:189], v[82:83], v[186:187], v[184:185] op_sel_hi:[0,1,1]
	v_cvt_pk_bf16_f32 v190, v188, v189
	v_and_b32_e32 v191, 63, v207
	v_lshl_add_u32 v191, v191, 1, v86
	ds_write_b32 v191, v190 offset:12528
	v_mfma_f32_16x16x32_bf16 v[36:39], v[68:71], v[36:39], 0
	s_waitcnt lgkmcnt(15)
	v_pk_fma_f32 v[184:185], v[82:83], v[188:189], v[140:141] op_sel:[1,1,0] op_sel_hi:[1,0,1] neg_lo:[1,0,0]
	v_pk_fma_f32 v[186:187], v[82:83], v[188:189], v[184:185] op_sel_hi:[0,1,1]
	v_cvt_pk_bf16_f32 v190, v186, v187
	ds_write_b32 v191, v190 offset:12256
	s_waitcnt lgkmcnt(15)
	v_pk_fma_f32 v[184:185], v[82:83], v[186:187], v[142:143] op_sel:[1,1,0] op_sel_hi:[1,0,1] neg_lo:[1,0,0]
	v_pk_fma_f32 v[188:189], v[82:83], v[186:187], v[184:185] op_sel_hi:[0,1,1]
	v_cvt_pk_bf16_f32 v190, v188, v189
	ds_write_b32 v191, v190 offset:11984
	s_waitcnt lgkmcnt(15)
	v_pk_fma_f32 v[184:185], v[82:83], v[188:189], v[144:145] op_sel:[1,1,0] op_sel_hi:[1,0,1] neg_lo:[1,0,0]
	v_pk_fma_f32 v[186:187], v[82:83], v[188:189], v[184:185] op_sel_hi:[0,1,1]
	v_cvt_pk_bf16_f32 v190, v186, v187
	ds_write_b32 v191, v190 offset:11712
	s_waitcnt lgkmcnt(15)
	v_pk_fma_f32 v[184:185], v[82:83], v[186:187], v[146:147] op_sel:[1,1,0] op_sel_hi:[1,0,1] neg_lo:[1,0,0]
	v_pk_fma_f32 v[188:189], v[82:83], v[186:187], v[184:185] op_sel_hi:[0,1,1]
	v_cvt_pk_bf16_f32 v190, v188, v189
	ds_write_b32 v191, v190 offset:11440
	s_waitcnt lgkmcnt(15)
	v_pk_fma_f32 v[184:185], v[82:83], v[188:189], v[148:149] op_sel:[1,1,0] op_sel_hi:[1,0,1] neg_lo:[1,0,0]
	v_pk_fma_f32 v[186:187], v[82:83], v[188:189], v[184:185] op_sel_hi:[0,1,1]
	v_cvt_pk_bf16_f32 v190, v186, v187
	ds_write_b32 v191, v190 offset:11168
	s_waitcnt lgkmcnt(15)
	v_pk_fma_f32 v[184:185], v[82:83], v[186:187], v[150:151] op_sel:[1,1,0] op_sel_hi:[1,0,1] neg_lo:[1,0,0]
	v_pk_fma_f32 v[188:189], v[82:83], v[186:187], v[184:185] op_sel_hi:[0,1,1]
	v_cvt_pk_bf16_f32 v190, v188, v189
	ds_write_b32 v191, v190 offset:10896
	s_waitcnt lgkmcnt(15)
	v_pk_fma_f32 v[184:185], v[82:83], v[188:189], v[152:153] op_sel:[1,1,0] op_sel_hi:[1,0,1] neg_lo:[1,0,0]
	v_pk_fma_f32 v[186:187], v[82:83], v[188:189], v[184:185] op_sel_hi:[0,1,1]
	v_cvt_pk_bf16_f32 v190, v186, v187
	ds_write_b32 v191, v190 offset:10624
	s_waitcnt lgkmcnt(15)
	v_pk_fma_f32 v[184:185], v[82:83], v[186:187], v[154:155] op_sel:[1,1,0] op_sel_hi:[1,0,1] neg_lo:[1,0,0]
	v_pk_fma_f32 v[188:189], v[82:83], v[186:187], v[184:185] op_sel_hi:[0,1,1]
	v_cvt_pk_bf16_f32 v190, v188, v189
	ds_write_b32 v191, v190 offset:10352
	s_waitcnt lgkmcnt(15)
	v_pk_fma_f32 v[184:185], v[82:83], v[188:189], v[156:157] op_sel:[1,1,0] op_sel_hi:[1,0,1] neg_lo:[1,0,0]
	v_pk_fma_f32 v[186:187], v[82:83], v[188:189], v[184:185] op_sel_hi:[0,1,1]
	v_cvt_pk_bf16_f32 v190, v186, v187
	ds_write_b32 v191, v190 offset:10080
	s_waitcnt lgkmcnt(15)
	v_pk_fma_f32 v[184:185], v[82:83], v[186:187], v[158:159] op_sel:[1,1,0] op_sel_hi:[1,0,1] neg_lo:[1,0,0]
	v_pk_fma_f32 v[188:189], v[82:83], v[186:187], v[184:185] op_sel_hi:[0,1,1]
	v_cvt_pk_bf16_f32 v190, v188, v189
	ds_write_b32 v191, v190 offset:9808
	s_waitcnt lgkmcnt(15)
	v_pk_fma_f32 v[184:185], v[82:83], v[188:189], v[160:161] op_sel:[1,1,0] op_sel_hi:[1,0,1] neg_lo:[1,0,0]
	v_pk_fma_f32 v[186:187], v[82:83], v[188:189], v[184:185] op_sel_hi:[0,1,1]
	v_cvt_pk_bf16_f32 v190, v186, v187
	ds_write_b32 v191, v190 offset:9536
	s_waitcnt lgkmcnt(15)
	v_pk_fma_f32 v[184:185], v[82:83], v[186:187], v[162:163] op_sel:[1,1,0] op_sel_hi:[1,0,1] neg_lo:[1,0,0]
	v_pk_fma_f32 v[188:189], v[82:83], v[186:187], v[184:185] op_sel_hi:[0,1,1]
	v_cvt_pk_bf16_f32 v190, v188, v189
	ds_write_b32 v191, v190 offset:9264
	s_waitcnt lgkmcnt(15)
	v_pk_fma_f32 v[184:185], v[82:83], v[188:189], v[164:165] op_sel:[1,1,0] op_sel_hi:[1,0,1] neg_lo:[1,0,0]
	v_pk_fma_f32 v[186:187], v[82:83], v[188:189], v[184:185] op_sel_hi:[0,1,1]
	v_cvt_pk_bf16_f32 v190, v186, v187
	ds_write_b32 v191, v190 offset:8992
	s_waitcnt lgkmcnt(15)
	v_pk_fma_f32 v[184:185], v[82:83], v[186:187], v[166:167] op_sel:[1,1,0] op_sel_hi:[1,0,1] neg_lo:[1,0,0]
	v_pk_fma_f32 v[188:189], v[82:83], v[186:187], v[184:185] op_sel_hi:[0,1,1]
	v_cvt_pk_bf16_f32 v190, v188, v189
	ds_write_b32 v191, v190 offset:8720
	s_waitcnt lgkmcnt(15)
	v_pk_fma_f32 v[184:185], v[82:83], v[188:189], v[168:169] op_sel:[1,1,0] op_sel_hi:[1,0,1] neg_lo:[1,0,0]
	v_pk_fma_f32 v[186:187], v[82:83], v[188:189], v[184:185] op_sel_hi:[0,1,1]
	v_mov_b32_e32 v103, v186
	v_mov_b32_e32 v112, v187
	v_cvt_pk_bf16_f32 v190, v186, v187
	ds_write_b32 v191, v190 offset:8448
	s_waitcnt vmcnt(0) lgkmcnt(0)
	ds_read_b128 v[72:75], v81 offset:8448
	ds_read_b128 v[104:107], v81 offset:8512
	s_waitcnt lgkmcnt(1)
	v_mfma_f32_16x16x32_bf16 v[72:75], v[72:75], v[32:35], 0
	s_waitcnt lgkmcnt(0)
	v_mfma_f32_16x16x32_bf16 v[72:75], v[104:107], v[28:31], v[72:75]
	ds_read_b128 v[104:107], v81 offset:8576
	s_waitcnt lgkmcnt(0)
	v_mfma_f32_16x16x32_bf16 v[72:75], v[104:107], v[24:27], v[72:75]
	ds_read_b128 v[104:107], v81 offset:8640
	s_waitcnt lgkmcnt(0)
	v_mfma_f32_16x16x32_bf16 v[72:75], v[104:107], v[20:23], v[72:75]
	v_mfma_f32_16x16x32_bf16 v[104:107], v[76:79], v[40:43], 0
	s_nop 7
	ds_write2_b32 v88, v104, v108 offset1:16
	ds_write2_b32 v88, v105, v109 offset0:132 offset1:148
	ds_write2_b32 v89, v106, v110 offset0:8 offset1:24
	ds_write2_b32 v89, v107, v111 offset0:140 offset1:156
	v_mfma_f32_16x16x32_bf16 v[104:107], v[76:79], v[48:51], 0
	v_mfma_f32_16x16x32_bf16 v[108:111], v[76:79], v[44:47], 0
	s_nop 7
	ds_write2_b32 v88, v104, v108 offset0:32 offset1:48
	ds_write2_b32 v88, v105, v109 offset0:164 offset1:180
	ds_write2_b32 v89, v106, v110 offset0:40 offset1:56
	ds_write2_b32 v89, v107, v111 offset0:172 offset1:188
	v_mfma_f32_16x16x32_bf16 v[104:107], v[76:79], v[56:59], 0
	v_mfma_f32_16x16x32_bf16 v[108:111], v[76:79], v[52:55], 0
	s_nop 7
	ds_write2_b32 v88, v104, v108 offset0:64 offset1:80
	ds_write2_b32 v88, v105, v109 offset0:196 offset1:212
	ds_write2_b32 v89, v106, v110 offset0:72 offset1:88
	ds_write2_b32 v89, v107, v111 offset0:204 offset1:220
	v_mfma_f32_16x16x32_bf16 v[104:107], v[76:79], v[64:67], 0
	v_mfma_f32_16x16x32_bf16 v[76:79], v[76:79], v[60:63], 0
	s_nop 7
	ds_write2_b32 v88, v104, v76 offset0:96 offset1:112
	ds_write2_b32 v88, v105, v77 offset0:228 offset1:244
	ds_write2_b32 v89, v106, v78 offset0:104 offset1:120
	ds_write2_b32 v89, v107, v79 offset0:236 offset1:252
	s_waitcnt vmcnt(0) lgkmcnt(0)
	ds_read2st64_b32 v[76:77], v91 offset0:30 offset1:31
	ds_read2st64_b32 v[140:141], v84 offset0:28 offset1:29
	ds_read2st64_b32 v[142:143], v85 offset0:26 offset1:27
	ds_read2st64_b32 v[144:145], v92 offset0:24 offset1:25
	ds_read2st64_b32 v[146:147], v93 offset0:22 offset1:23
	ds_read2st64_b32 v[148:149], v94 offset0:20 offset1:21
	ds_read2st64_b32 v[150:151], v95 offset0:18 offset1:19
	ds_read2st64_b32 v[152:153], v96 offset0:16 offset1:17
	ds_read2st64_b32 v[154:155], v97 offset0:14 offset1:15
	ds_read2st64_b32 v[156:157], v98 offset0:12 offset1:13
	ds_read2st64_b32 v[158:159], v99 offset0:10 offset1:11
	ds_read2st64_b32 v[160:161], v100 offset0:8 offset1:9
	ds_read2st64_b32 v[162:163], v101 offset0:6 offset1:7
	ds_read2st64_b32 v[164:165], v102 offset0:4 offset1:5
	ds_read2_b32 v[166:167], v87 offset0:132 offset1:196
	ds_read2st64_b32 v[168:169], v87 offset1:1
	v_mov_b32_e32 v186, v103
	v_mov_b32_e32 v187, v112
	v_mfma_f32_16x16x32_bf16 v[40:43], v[68:71], v[40:43], 0
	s_waitcnt lgkmcnt(15)
	v_pk_fma_f32 v[184:185], v[82:83], v[186:187], v[76:77] op_sel:[1,1,0] op_sel_hi:[1,0,1] neg_lo:[1,0,0]
	v_pk_fma_f32 v[188:189], v[82:83], v[186:187], v[184:185] op_sel_hi:[0,1,1]
	v_cvt_pk_bf16_f32 v190, v188, v189
	v_and_b32_e32 v191, 63, v207
	v_lshl_add_u32 v191, v191, 1, v86
	ds_write_b32 v191, v190 offset:12528
	s_waitcnt lgkmcnt(15)
	v_pk_fma_f32 v[184:185], v[82:83], v[188:189], v[140:141] op_sel:[1,1,0] op_sel_hi:[1,0,1] neg_lo:[1,0,0]
	v_pk_fma_f32 v[186:187], v[82:83], v[188:189], v[184:185] op_sel_hi:[0,1,1]
	v_cvt_pk_bf16_f32 v190, v186, v187
	ds_write_b32 v191, v190 offset:12256
	s_waitcnt lgkmcnt(15)
	v_pk_fma_f32 v[184:185], v[82:83], v[186:187], v[142:143] op_sel:[1,1,0] op_sel_hi:[1,0,1] neg_lo:[1,0,0]
	v_pk_fma_f32 v[188:189], v[82:83], v[186:187], v[184:185] op_sel_hi:[0,1,1]
	v_cvt_pk_bf16_f32 v190, v188, v189
	ds_write_b32 v191, v190 offset:11984
	s_waitcnt lgkmcnt(15)
	v_pk_fma_f32 v[184:185], v[82:83], v[188:189], v[144:145] op_sel:[1,1,0] op_sel_hi:[1,0,1] neg_lo:[1,0,0]
	v_pk_fma_f32 v[186:187], v[82:83], v[188:189], v[184:185] op_sel_hi:[0,1,1]
	v_cvt_pk_bf16_f32 v190, v186, v187
	ds_write_b32 v191, v190 offset:11712
	s_waitcnt lgkmcnt(15)
	v_pk_fma_f32 v[184:185], v[82:83], v[186:187], v[146:147] op_sel:[1,1,0] op_sel_hi:[1,0,1] neg_lo:[1,0,0]
	v_pk_fma_f32 v[188:189], v[82:83], v[186:187], v[184:185] op_sel_hi:[0,1,1]
	v_cvt_pk_bf16_f32 v190, v188, v189
	ds_write_b32 v191, v190 offset:11440
	s_waitcnt lgkmcnt(15)
	v_pk_fma_f32 v[184:185], v[82:83], v[188:189], v[148:149] op_sel:[1,1,0] op_sel_hi:[1,0,1] neg_lo:[1,0,0]
	v_pk_fma_f32 v[186:187], v[82:83], v[188:189], v[184:185] op_sel_hi:[0,1,1]
	v_cvt_pk_bf16_f32 v190, v186, v187
	ds_write_b32 v191, v190 offset:11168
	s_waitcnt lgkmcnt(15)
	v_pk_fma_f32 v[184:185], v[82:83], v[186:187], v[150:151] op_sel:[1,1,0] op_sel_hi:[1,0,1] neg_lo:[1,0,0]
	v_pk_fma_f32 v[188:189], v[82:83], v[186:187], v[184:185] op_sel_hi:[0,1,1]
	v_cvt_pk_bf16_f32 v190, v188, v189
	ds_write_b32 v191, v190 offset:10896
	s_waitcnt lgkmcnt(15)
	v_pk_fma_f32 v[184:185], v[82:83], v[188:189], v[152:153] op_sel:[1,1,0] op_sel_hi:[1,0,1] neg_lo:[1,0,0]
	v_pk_fma_f32 v[186:187], v[82:83], v[188:189], v[184:185] op_sel_hi:[0,1,1]
	v_cvt_pk_bf16_f32 v190, v186, v187
	ds_write_b32 v191, v190 offset:10624
	s_waitcnt lgkmcnt(15)
	v_pk_fma_f32 v[184:185], v[82:83], v[186:187], v[154:155] op_sel:[1,1,0] op_sel_hi:[1,0,1] neg_lo:[1,0,0]
	v_pk_fma_f32 v[188:189], v[82:83], v[186:187], v[184:185] op_sel_hi:[0,1,1]
	v_cvt_pk_bf16_f32 v190, v188, v189
	ds_write_b32 v191, v190 offset:10352
	s_waitcnt lgkmcnt(15)
	v_pk_fma_f32 v[184:185], v[82:83], v[188:189], v[156:157] op_sel:[1,1,0] op_sel_hi:[1,0,1] neg_lo:[1,0,0]
	v_pk_fma_f32 v[186:187], v[82:83], v[188:189], v[184:185] op_sel_hi:[0,1,1]
	v_cvt_pk_bf16_f32 v190, v186, v187
	ds_write_b32 v191, v190 offset:10080
	s_waitcnt lgkmcnt(15)
	v_pk_fma_f32 v[184:185], v[82:83], v[186:187], v[158:159] op_sel:[1,1,0] op_sel_hi:[1,0,1] neg_lo:[1,0,0]
	v_pk_fma_f32 v[188:189], v[82:83], v[186:187], v[184:185] op_sel_hi:[0,1,1]
	v_cvt_pk_bf16_f32 v190, v188, v189
	ds_write_b32 v191, v190 offset:9808
	s_waitcnt lgkmcnt(15)
	v_pk_fma_f32 v[184:185], v[82:83], v[188:189], v[160:161] op_sel:[1,1,0] op_sel_hi:[1,0,1] neg_lo:[1,0,0]
	v_pk_fma_f32 v[186:187], v[82:83], v[188:189], v[184:185] op_sel_hi:[0,1,1]
	v_cvt_pk_bf16_f32 v190, v186, v187
	ds_write_b32 v191, v190 offset:9536
	s_waitcnt lgkmcnt(15)
	v_pk_fma_f32 v[184:185], v[82:83], v[186:187], v[162:163] op_sel:[1,1,0] op_sel_hi:[1,0,1] neg_lo:[1,0,0]
	v_pk_fma_f32 v[188:189], v[82:83], v[186:187], v[184:185] op_sel_hi:[0,1,1]
	v_cvt_pk_bf16_f32 v190, v188, v189
	ds_write_b32 v191, v190 offset:9264
	s_waitcnt lgkmcnt(15)
	v_pk_fma_f32 v[184:185], v[82:83], v[188:189], v[164:165] op_sel:[1,1,0] op_sel_hi:[1,0,1] neg_lo:[1,0,0]
	v_pk_fma_f32 v[186:187], v[82:83], v[188:189], v[184:185] op_sel_hi:[0,1,1]
	v_cvt_pk_bf16_f32 v190, v186, v187
	ds_write_b32 v191, v190 offset:8992
	s_waitcnt lgkmcnt(15)
	v_pk_fma_f32 v[184:185], v[82:83], v[186:187], v[166:167] op_sel:[1,1,0] op_sel_hi:[1,0,1] neg_lo:[1,0,0]
	v_pk_fma_f32 v[188:189], v[82:83], v[186:187], v[184:185] op_sel_hi:[0,1,1]
	v_cvt_pk_bf16_f32 v190, v188, v189
	ds_write_b32 v191, v190 offset:8720
	s_waitcnt lgkmcnt(15)
	v_pk_fma_f32 v[184:185], v[82:83], v[188:189], v[168:169] op_sel:[1,1,0] op_sel_hi:[1,0,1] neg_lo:[1,0,0]
	v_pk_fma_f32 v[186:187], v[82:83], v[188:189], v[184:185] op_sel_hi:[0,1,1]
	v_mov_b32_e32 v103, v186
	v_mov_b32_e32 v108, v187
	v_cvt_pk_bf16_f32 v190, v186, v187
	ds_write_b32 v191, v190 offset:8448
	s_waitcnt vmcnt(0) lgkmcnt(0)
	ds_read_b128 v[76:79], v81 offset:8448
	ds_read_b128 v[104:107], v81 offset:8512
	s_waitcnt lgkmcnt(1)
	v_mfma_f32_16x16x32_bf16 v[76:79], v[76:79], v[32:35], 0
	s_waitcnt lgkmcnt(0)
	v_mfma_f32_16x16x32_bf16 v[76:79], v[104:107], v[28:31], v[76:79]
	ds_read_b128 v[104:107], v81 offset:8576
	s_waitcnt lgkmcnt(0)
	v_mfma_f32_16x16x32_bf16 v[76:79], v[104:107], v[24:27], v[76:79]
	ds_read_b128 v[104:107], v81 offset:8640
	ds_write2_b32 v88, v40, v36 offset1:16
	ds_write2_b32 v88, v41, v37 offset0:132 offset1:148
	ds_write2_b32 v89, v42, v38 offset0:8 offset1:24
	ds_write2_b32 v89, v43, v39 offset0:140 offset1:156
	v_mfma_f32_16x16x32_bf16 v[36:39], v[68:71], v[48:51], 0
	v_mfma_f32_16x16x32_bf16 v[40:43], v[68:71], v[44:47], 0
	s_nop 7
	ds_write2_b32 v88, v36, v40 offset0:32 offset1:48
	ds_write2_b32 v88, v37, v41 offset0:164 offset1:180
	ds_write2_b32 v89, v38, v42 offset0:40 offset1:56
	ds_write2_b32 v89, v39, v43 offset0:172 offset1:188
	v_mfma_f32_16x16x32_bf16 v[36:39], v[68:71], v[56:59], 0
	v_mfma_f32_16x16x32_bf16 v[40:43], v[68:71], v[52:55], 0
	s_nop 7
	ds_write2_b32 v88, v36, v40 offset0:64 offset1:80
	ds_write2_b32 v88, v37, v41 offset0:196 offset1:212
	ds_write2_b32 v89, v38, v42 offset0:72 offset1:88
	ds_write2_b32 v89, v39, v43 offset0:204 offset1:220
	v_mfma_f32_16x16x32_bf16 v[36:39], v[68:71], v[64:67], 0
	v_mfma_f32_16x16x32_bf16 v[40:43], v[68:71], v[60:63], 0
	s_nop 7
	ds_write2_b32 v88, v36, v40 offset0:96 offset1:112
	ds_write2_b32 v88, v37, v41 offset0:228 offset1:244
	ds_write2_b32 v89, v38, v42 offset0:104 offset1:120
	ds_write2_b32 v89, v39, v43 offset0:236 offset1:252
	s_waitcnt vmcnt(0) lgkmcnt(0)
	ds_read2st64_b32 v[36:37], v91 offset0:30 offset1:31
	ds_read2st64_b32 v[140:141], v84 offset0:28 offset1:29
	ds_read2st64_b32 v[142:143], v85 offset0:26 offset1:27
	ds_read2st64_b32 v[144:145], v92 offset0:24 offset1:25
	ds_read2st64_b32 v[146:147], v93 offset0:22 offset1:23
	ds_read2st64_b32 v[148:149], v94 offset0:20 offset1:21
	ds_read2st64_b32 v[150:151], v95 offset0:18 offset1:19
	ds_read2st64_b32 v[152:153], v96 offset0:16 offset1:17
	ds_read2st64_b32 v[154:155], v97 offset0:14 offset1:15
	ds_read2st64_b32 v[156:157], v98 offset0:12 offset1:13
	ds_read2st64_b32 v[158:159], v99 offset0:10 offset1:11
	ds_read2st64_b32 v[160:161], v100 offset0:8 offset1:9
	ds_read2st64_b32 v[162:163], v101 offset0:6 offset1:7
	ds_read2st64_b32 v[164:165], v102 offset0:4 offset1:5
	ds_read2_b32 v[166:167], v87 offset0:132 offset1:196
	ds_read2st64_b32 v[168:169], v87 offset1:1
	v_mov_b32_e32 v186, v103
	v_mov_b32_e32 v187, v108
	s_waitcnt lgkmcnt(15)
	v_mfma_f32_16x16x32_bf16 v[76:79], v[104:107], v[20:23], v[76:79]
	v_pk_fma_f32 v[184:185], v[82:83], v[186:187], v[36:37] op_sel:[1,1,0] op_sel_hi:[1,0,1] neg_lo:[1,0,0]
	v_pk_fma_f32 v[188:189], v[82:83], v[186:187], v[184:185] op_sel_hi:[0,1,1]
	v_cvt_pk_bf16_f32 v190, v188, v189
	v_and_b32_e32 v191, 63, v207
	v_lshl_add_u32 v191, v191, 1, v86
	ds_write_b32 v191, v190 offset:12528
	s_waitcnt lgkmcnt(15)
	v_pk_fma_f32 v[184:185], v[82:83], v[188:189], v[140:141] op_sel:[1,1,0] op_sel_hi:[1,0,1] neg_lo:[1,0,0]
	v_pk_fma_f32 v[186:187], v[82:83], v[188:189], v[184:185] op_sel_hi:[0,1,1]
	v_cvt_pk_bf16_f32 v190, v186, v187
	ds_write_b32 v191, v190 offset:12256
	s_waitcnt lgkmcnt(15)
	v_pk_fma_f32 v[184:185], v[82:83], v[186:187], v[142:143] op_sel:[1,1,0] op_sel_hi:[1,0,1] neg_lo:[1,0,0]
	v_pk_fma_f32 v[188:189], v[82:83], v[186:187], v[184:185] op_sel_hi:[0,1,1]
	v_cvt_pk_bf16_f32 v190, v188, v189
	ds_write_b32 v191, v190 offset:11984
	s_waitcnt lgkmcnt(15)
	v_pk_fma_f32 v[184:185], v[82:83], v[188:189], v[144:145] op_sel:[1,1,0] op_sel_hi:[1,0,1] neg_lo:[1,0,0]
	v_pk_fma_f32 v[186:187], v[82:83], v[188:189], v[184:185] op_sel_hi:[0,1,1]
	v_cvt_pk_bf16_f32 v190, v186, v187
	ds_write_b32 v191, v190 offset:11712
	s_waitcnt lgkmcnt(15)
	v_pk_fma_f32 v[184:185], v[82:83], v[186:187], v[146:147] op_sel:[1,1,0] op_sel_hi:[1,0,1] neg_lo:[1,0,0]
	v_pk_fma_f32 v[188:189], v[82:83], v[186:187], v[184:185] op_sel_hi:[0,1,1]
	v_cvt_pk_bf16_f32 v190, v188, v189
	ds_write_b32 v191, v190 offset:11440
	s_waitcnt lgkmcnt(15)
	v_pk_fma_f32 v[184:185], v[82:83], v[188:189], v[148:149] op_sel:[1,1,0] op_sel_hi:[1,0,1] neg_lo:[1,0,0]
	v_pk_fma_f32 v[186:187], v[82:83], v[188:189], v[184:185] op_sel_hi:[0,1,1]
	v_cvt_pk_bf16_f32 v190, v186, v187
	ds_write_b32 v191, v190 offset:11168
	s_waitcnt lgkmcnt(15)
	v_pk_fma_f32 v[184:185], v[82:83], v[186:187], v[150:151] op_sel:[1,1,0] op_sel_hi:[1,0,1] neg_lo:[1,0,0]
	v_pk_fma_f32 v[188:189], v[82:83], v[186:187], v[184:185] op_sel_hi:[0,1,1]
	v_cvt_pk_bf16_f32 v190, v188, v189
	ds_write_b32 v191, v190 offset:10896
	s_waitcnt lgkmcnt(15)
	v_pk_fma_f32 v[184:185], v[82:83], v[188:189], v[152:153] op_sel:[1,1,0] op_sel_hi:[1,0,1] neg_lo:[1,0,0]
	v_pk_fma_f32 v[186:187], v[82:83], v[188:189], v[184:185] op_sel_hi:[0,1,1]
	v_cvt_pk_bf16_f32 v190, v186, v187
	ds_write_b32 v191, v190 offset:10624
	s_waitcnt lgkmcnt(15)
	v_pk_fma_f32 v[184:185], v[82:83], v[186:187], v[154:155] op_sel:[1,1,0] op_sel_hi:[1,0,1] neg_lo:[1,0,0]
	v_pk_fma_f32 v[188:189], v[82:83], v[186:187], v[184:185] op_sel_hi:[0,1,1]
	v_cvt_pk_bf16_f32 v190, v188, v189
	ds_write_b32 v191, v190 offset:10352
	s_waitcnt lgkmcnt(15)
	v_pk_fma_f32 v[184:185], v[82:83], v[188:189], v[156:157] op_sel:[1,1,0] op_sel_hi:[1,0,1] neg_lo:[1,0,0]
	v_pk_fma_f32 v[186:187], v[82:83], v[188:189], v[184:185] op_sel_hi:[0,1,1]
	v_cvt_pk_bf16_f32 v190, v186, v187
	ds_write_b32 v191, v190 offset:10080
	s_waitcnt lgkmcnt(15)
	v_pk_fma_f32 v[184:185], v[82:83], v[186:187], v[158:159] op_sel:[1,1,0] op_sel_hi:[1,0,1] neg_lo:[1,0,0]
	v_pk_fma_f32 v[188:189], v[82:83], v[186:187], v[184:185] op_sel_hi:[0,1,1]
	v_cvt_pk_bf16_f32 v190, v188, v189
	ds_write_b32 v191, v190 offset:9808
	s_waitcnt lgkmcnt(15)
	v_pk_fma_f32 v[184:185], v[82:83], v[188:189], v[160:161] op_sel:[1,1,0] op_sel_hi:[1,0,1] neg_lo:[1,0,0]
	v_pk_fma_f32 v[186:187], v[82:83], v[188:189], v[184:185] op_sel_hi:[0,1,1]
	v_cvt_pk_bf16_f32 v190, v186, v187
	ds_write_b32 v191, v190 offset:9536
	s_waitcnt lgkmcnt(15)
	v_pk_fma_f32 v[184:185], v[82:83], v[186:187], v[162:163] op_sel:[1,1,0] op_sel_hi:[1,0,1] neg_lo:[1,0,0]
	v_pk_fma_f32 v[188:189], v[82:83], v[186:187], v[184:185] op_sel_hi:[0,1,1]
	v_cvt_pk_bf16_f32 v190, v188, v189
	ds_write_b32 v191, v190 offset:9264
	s_waitcnt lgkmcnt(15)
	v_pk_fma_f32 v[184:185], v[82:83], v[188:189], v[164:165] op_sel:[1,1,0] op_sel_hi:[1,0,1] neg_lo:[1,0,0]
	v_pk_fma_f32 v[186:187], v[82:83], v[188:189], v[184:185] op_sel_hi:[0,1,1]
	v_cvt_pk_bf16_f32 v190, v186, v187
	ds_write_b32 v191, v190 offset:8992
	s_waitcnt lgkmcnt(15)
	v_pk_fma_f32 v[184:185], v[82:83], v[186:187], v[166:167] op_sel:[1,1,0] op_sel_hi:[1,0,1] neg_lo:[1,0,0]
	v_pk_fma_f32 v[188:189], v[82:83], v[186:187], v[184:185] op_sel_hi:[0,1,1]
	v_cvt_pk_bf16_f32 v190, v188, v189
	ds_write_b32 v191, v190 offset:8720
	s_waitcnt lgkmcnt(15)
	v_pk_fma_f32 v[184:185], v[82:83], v[188:189], v[168:169] op_sel:[1,1,0] op_sel_hi:[1,0,1] neg_lo:[1,0,0]
	v_pk_fma_f32 v[186:187], v[82:83], v[188:189], v[184:185] op_sel_hi:[0,1,1]
	v_mov_b32_e32 v36, v186
	v_mov_b32_e32 v37, v187
	v_cvt_pk_bf16_f32 v190, v186, v187
	ds_write_b32 v191, v190 offset:8448
	s_waitcnt vmcnt(0) lgkmcnt(0)
	ds_read_b128 v[36:39], v81 offset:8448
	s_waitcnt lgkmcnt(0)
	v_mfma_f32_16x16x32_bf16 v[32:35], v[36:39], v[32:35], 0
	ds_read_b128 v[36:39], v81 offset:8512
	s_waitcnt lgkmcnt(0)
	v_mfma_f32_16x16x32_bf16 v[28:31], v[36:39], v[28:31], v[32:35]
	s_nop 4
	ds_read_b128 v[32:35], v81 offset:8576
	s_waitcnt lgkmcnt(0)
	v_mfma_f32_16x16x32_bf16 v[24:27], v[32:35], v[24:27], v[28:31]
	s_nop 2
	ds_read_b128 v[28:31], v81 offset:8640
	s_waitcnt lgkmcnt(0)
	v_mfma_f32_16x16x32_bf16 v[20:23], v[28:31], v[20:23], v[24:27]
	s_nop 7
	v_pk_add_f32 v[24:25], v[0:1], v[20:21]
	v_and_or_b32 v0, v90, 15, v80
	v_add_u32_e32 v20, s6, v0
	v_ashrrev_i32_e32 v21, 31, v20
	v_lshrrev_b32_e32 v1, 2, v90
	v_lshl_add_u64 v[20:21], v[20:21], 2, s[76:77]
	v_and_b32_e32 v1, 12, v1
	global_load_dword v28, v[20:21], off
	v_add_u32_e32 v20, s8, v1
	v_ashrrev_i32_e32 v21, 31, v20
	v_ashrrev_i32_e32 v1, 31, v0
	v_lshlrev_b64 v[26:27], 9, v[20:21]
	v_lshl_add_u64 v[26:27], v[26:27], 0, v[0:1]
	v_lshl_add_u64 v[30:31], v[26:27], 1, s[36:37]
	global_load_ushort v29, v[30:31], off
	global_load_ushort v141, v[30:31], off offset:1024
	global_load_ushort v142, v[30:31], off offset:2048
	global_load_ushort v143, v[30:31], off offset:3072
	s_mov_b64 s[0:1], 0x4000
	v_lshl_add_u64 v[156:157], v[30:31], 0, s[0:1]
	global_load_ushort v144, v[156:157], off
	global_load_ushort v145, v[156:157], off offset:1024
	global_load_ushort v146, v[156:157], off offset:2048
	global_load_ushort v147, v[156:157], off offset:3072
	s_mov_b64 s[0:1], 0x8000
	v_lshl_add_u64 v[158:159], v[30:31], 0, s[0:1]
	global_load_ushort v148, v[158:159], off
	global_load_ushort v149, v[158:159], off offset:1024
	global_load_ushort v150, v[158:159], off offset:2048
	global_load_ushort v151, v[158:159], off offset:3072
	s_mov_b64 s[0:1], 0xc000
	v_lshl_add_u64 v[160:161], v[30:31], 0, s[0:1]
	global_load_ushort v152, v[160:161], off
	global_load_ushort v153, v[160:161], off offset:1024
	global_load_ushort v154, v[160:161], off offset:2048
	global_load_ushort v155, v[160:161], off offset:3072
	s_waitcnt vmcnt(0) lgkmcnt(0)
	v_lshlrev_b32_e32 v29, 16, v29
	v_fma_f32 v24, v28, v29, v24
	v_mul_f32_e32 v29, 0x3d372713, v24
	v_mul_f32_e32 v29, v24, v29
	v_fma_f32 v29, v24, v29, v24
	v_mul_f32_e32 v29, 0x3f4c422a, v29
	v_cmp_nlt_f32_e64 s[0:1], |v29|, s10
	s_and_saveexec_b64 s[2:3], s[0:1]
	s_xor_b64 s[0:1], exec, s[2:3]
	s_cbranch_execz .LBB0_1813
	v_add_f32_e64 v30, |v29|, |v29|
	v_mul_f32_e32 v31, 0x3fb8aa3b, v30
	v_rndne_f32_e32 v32, v31
	s_mov_b32 s2, 0x3fb8aa3b
	v_sub_f32_e32 v33, v31, v32
	v_fma_f32 v31, v30, s2, -v31
	v_fmac_f32_e32 v31, 0x32a5705f, v30
	v_add_f32_e32 v31, v33, v31
	v_cvt_i32_f32_e32 v32, v32
	v_exp_f32_e32 v31, v31
	s_mov_b32 s2, 0xc2ce8ed0
	v_cmp_ngt_f32_e32 vcc, s2, v30
	s_mov_b32 s2, 0x42b17218
	v_ldexp_f32 v31, v31, v32
	v_cndmask_b32_e32 v31, 0, v31, vcc
	v_cmp_nlt_f32_e32 vcc, s2, v30
	s_nop 1
	v_cndmask_b32_e32 v30, v235, v31, vcc
	v_add_f32_e32 v30, 1.0, v30
	v_rcp_f32_e32 v30, v30
	s_nop 0
	v_fma_f32 v30, v30, -2.0, 1.0
